# BO2 + second MFMA run of each block starts with the pair sharing an operand with the first run's last MFMA
# speedup vs baseline: 1.0088x; 1.0057x over previous
; #define PG8_SB(B) __builtin_amdgcn_rcpf(1.f + expneg(B))
; #define PG8_SB(B) __builtin_amdgcn_rcpf(1.f + expneg(B))
; #define PG8_STAGE(bufoff, gbase, voff) do { _Pragma("unroll") for (int _i = 0; _i < 2; ++_i) \
;         __builtin_amdgcn_global_load_lds((const unsigned*)((const char*)(gbase) + (size_t)_i * qstep + (voff)[0]), (PG8_LAS unsigned*)(lds + (bufoff) + ldsw + _i * 8192), 16, 0, 0); } while (0)
; #define PG8_LDA(dst, b, h) do { _Pragma("unroll") for (int m = 0; m < 4; ++m) _Pragma("unroll") for (int k = 0; k < 2; ++k) dst[m][k] = *(const PG8_LAS bf16x8*)(lds + PG8_SA(b, h) + aoff + m * 2048 + k * 1024); } while (0)
; #define PG8_MMA(ai, bj, At, Bt) do { __builtin_amdgcn_s_setprio(1); _Pragma("unroll") for (int m = 0; m < 4; ++m) _Pragma("unroll") for (int n = 0; n < 2; ++n) _Pragma("unroll") for (int k = 0; k < 2; ++k) \
;         acc[ai][bj][m][n] = __builtin_amdgcn_mfma_f32_16x16x32_bf16(Bt[n][k], At[m][k], acc[ai][bj][m][n], 0, 0, 0); __builtin_amdgcn_s_setprio(0); } while (0)
; #define PG8_WAIT_V89() do { if constexpr (SLIVER) PG8_WAIT_V(9); else PG8_WAIT_V(8); } while (0)
; #define PG8_LDS_S(b) do { if constexpr (SLIVER) { Sf[0] = *(const PG8_LAS bf16x8*)(lds + STAGE_BYTES + (b) * 2048 + soff0); Sf[1] = *(const PG8_LAS bf16x8*)(lds + STAGE_BYTES + (b) * 2048 + (soff0 ^ 64)); } } while (0)
; #define PG8_WAIT_L(n) asm volatile("s_waitcnt lgkmcnt(" #n ")" ::: "memory")
; #define PG8_BAR __builtin_amdgcn_s_barrier()
; #define PG8_SCHED __builtin_amdgcn_sched_barrier(0)
; template <class Epi, class Sched, bool ALIGN_EPI = false, bool SP2 = false, bool SLIVER = false>
; __device__ __forceinline__ void gemm_phase(PG8_LAS unsigned char* lds, const Gemm g, const Sched& S, const Epi& E) {
;     ...
;             PG8_WAIT_V89(); PG8_WAIT_L(0); PG8_BAR; PG8_MMA(0, 0, At, B0); PG8_MMA(0, 1, At, B1); PG8_BAR; PG8_SCHED;
;             PG8_LDA(At, 0, 1); PG8_LDS_S(0); PG8_STAGE(PG8_SB(0, 0), b2, voffB); PG8_STAGE(PG8_SB(0, 1), b2 + hstep, voffB); PG8_STAGE(PG8_SA(0, 0), a2, voffA);
;             PG8_WAIT_V89(); PG8_WAIT_L(0); PG8_BAR; PG8_MMA(1, 0, At, B0); PG8_MMA(1, 1, At, B1); PG8_MMA_S(); PG8_BAR; PG8_SCHED;
.Lgin_skipw0:
	s_waitcnt lgkmcnt(0)
	s_setprio 1
	s_barrier
	v_mfma_f32_16x16x32_bf16 v[126:129], v[136:139], v[174:177], v[126:129]
	v_mfma_f32_16x16x32_bf16 v[126:129], v[140:143], v[180:183], v[126:129]
	v_mfma_f32_16x16x32_bf16 v[122:125], v[154:157], v[180:183], v[122:125]
	v_mfma_f32_16x16x32_bf16 v[122:125], v[150:153], v[174:177], v[122:125]
	v_mfma_f32_16x16x32_bf16 v[106:109], v[150:153], v[184:187], v[106:109]
	v_mfma_f32_16x16x32_bf16 v[106:109], v[154:157], v[188:191], v[106:109]
	v_mfma_f32_16x16x32_bf16 v[114:117], v[140:143], v[188:191], v[114:117]
	v_mfma_f32_16x16x32_bf16 v[114:117], v[136:139], v[184:187], v[114:117]
	v_mfma_f32_16x16x32_bf16 v[98:101], v[136:139], v[192:195], v[98:101]
	v_mfma_f32_16x16x32_bf16 v[98:101], v[140:143], v[196:199], v[98:101]
	v_mfma_f32_16x16x32_bf16 v[90:93], v[154:157], v[196:199], v[90:93]
	v_mfma_f32_16x16x32_bf16 v[90:93], v[150:153], v[192:195], v[90:93]
	v_mfma_f32_16x16x32_bf16 v[74:77], v[150:153], v[200:203], v[74:77]
	v_mfma_f32_16x16x32_bf16 v[74:77], v[154:157], v[210:213], v[74:77]
	v_mfma_f32_16x16x32_bf16 v[82:85], v[140:143], v[210:213], v[82:85]
	v_mfma_f32_16x16x32_bf16 v[82:85], v[136:139], v[200:203], v[82:85]
	s_setprio 0
	s_setprio 1
	v_mfma_f32_16x16x32_bf16 v[66:69], v[166:169], v[200:203], v[66:69]
	v_mfma_f32_16x16x32_bf16 v[66:69], v[170:173], v[210:213], v[66:69]
	v_mfma_f32_16x16x32_bf16 v[110:113], v[170:173], v[180:183], v[110:113]
	v_mfma_f32_16x16x32_bf16 v[110:113], v[166:169], v[174:177], v[110:113]
	v_mfma_f32_16x16x32_bf16 v[118:121], v[158:161], v[174:177], v[118:121]
	v_mfma_f32_16x16x32_bf16 v[118:121], v[162:165], v[180:183], v[118:121]
	v_mfma_f32_16x16x32_bf16 v[102:105], v[162:165], v[188:191], v[102:105]
	v_mfma_f32_16x16x32_bf16 v[102:105], v[158:161], v[184:187], v[102:105]
	v_mfma_f32_16x16x32_bf16 v[94:97], v[166:169], v[184:187], v[94:97]
	v_mfma_f32_16x16x32_bf16 v[94:97], v[170:173], v[188:191], v[94:97]
	v_mfma_f32_16x16x32_bf16 v[78:81], v[170:173], v[196:199], v[78:81]
	v_mfma_f32_16x16x32_bf16 v[78:81], v[166:169], v[192:195], v[78:81]
	v_mfma_f32_16x16x32_bf16 v[86:89], v[158:161], v[192:195], v[86:89]
	v_mfma_f32_16x16x32_bf16 v[86:89], v[162:165], v[196:199], v[86:89]
	v_mfma_f32_16x16x32_bf16 v[70:73], v[162:165], v[210:213], v[70:73]
	v_mfma_f32_16x16x32_bf16 v[70:73], v[158:161], v[200:203], v[70:73]
	s_barrier
	s_setprio 0
	s_add_i32 s77, s77, s53
	s_mov_b32 m0, s77
	ds_read_b128 v[174:177], v149 offset:16384
	ds_read_b128 v[180:183], v149 offset:17408
	ds_read_b128 v[184:187], v149 offset:18432
	ds_read_b128 v[188:191], v149 offset:19456
	ds_read_b128 v[192:195], v149 offset:20480
	ds_read_b128 v[196:199], v149 offset:21504
	ds_read_b128 v[200:203], v149 offset:22528
	ds_read_b128 v[210:213], v149 offset:23552
	global_load_lds_dwordx4 v132, s[78:79]
	s_add_i32 m0, s77, 0x2000
	s_add_i32 s77, s80, s53
	s_add_u32 s58, s78, 0x40000
	s_addc_u32 s59, s79, 0
	global_load_lds_dwordx4 v132, s[58:59]
	s_mov_b32 m0, s77
	s_nop 0
	s_add_u32 s60, s78, 0x80000
	s_addc_u32 s61, s79, 0
	global_load_lds_dwordx4 v132, s[60:61]
	s_add_i32 m0, s77, 0x2000
	s_nop 0
	s_add_u32 s36, s78, 0xc0000
	s_addc_u32 s37, s79, 0
	global_load_lds_dwordx4 v132, s[36:37]
	s_mov_b64 s[46:47], s[62:63]
	s_mov_b32 m0, s91
	s_nop 0
	global_load_lds_dwordx4 v130, s[46:47]
	s_mov_b32 m0, s50
	s_nop 0
	s_add_u32 s58, s46, 0x40000
	s_addc_u32 s59, s47, 0
	global_load_lds_dwordx4 v130, s[58:59]
	s_cmp_eq_u32 s76, s101
	s_cbranch_scc1 .Lgin_skipw1
	s_waitcnt vmcnt(8)
.Lgin_skipw1:
	s_waitcnt lgkmcnt(0)
	s_setprio 1
	s_barrier
	v_mfma_f32_16x16x32_bf16 v[62:65], v[136:139], v[174:177], v[62:65]
	v_mfma_f32_16x16x32_bf16 v[62:65], v[140:143], v[180:183], v[62:65]
	v_mfma_f32_16x16x32_bf16 v[58:61], v[154:157], v[180:183], v[58:61]
	v_mfma_f32_16x16x32_bf16 v[58:61], v[150:153], v[174:177], v[58:61]
	v_mfma_f32_16x16x32_bf16 v[42:45], v[150:153], v[184:187], v[42:45]
	v_mfma_f32_16x16x32_bf16 v[42:45], v[154:157], v[188:191], v[42:45]
	v_mfma_f32_16x16x32_bf16 v[50:53], v[140:143], v[188:191], v[50:53]
	v_mfma_f32_16x16x32_bf16 v[50:53], v[136:139], v[184:187], v[50:53]
	v_mfma_f32_16x16x32_bf16 v[34:37], v[136:139], v[192:195], v[34:37]
	v_mfma_f32_16x16x32_bf16 v[34:37], v[140:143], v[196:199], v[34:37]
	v_mfma_f32_16x16x32_bf16 v[26:29], v[154:157], v[196:199], v[26:29]
	v_mfma_f32_16x16x32_bf16 v[26:29], v[150:153], v[192:195], v[26:29]
	v_mfma_f32_16x16x32_bf16 v[10:13], v[150:153], v[200:203], v[10:13]
	v_mfma_f32_16x16x32_bf16 v[10:13], v[154:157], v[210:213], v[10:13]
	v_mfma_f32_16x16x32_bf16 v[18:21], v[140:143], v[210:213], v[18:21]
	v_mfma_f32_16x16x32_bf16 v[18:21], v[136:139], v[200:203], v[18:21]
	s_setprio 0
	s_setprio 1
	v_mfma_f32_16x16x32_bf16 v[2:5], v[166:169], v[200:203], v[2:5]
	v_mfma_f32_16x16x32_bf16 v[2:5], v[170:173], v[210:213], v[2:5]
	v_mfma_f32_16x16x32_bf16 v[46:49], v[170:173], v[180:183], v[46:49]
	v_mfma_f32_16x16x32_bf16 v[46:49], v[166:169], v[174:177], v[46:49]
	v_mfma_f32_16x16x32_bf16 v[54:57], v[158:161], v[174:177], v[54:57]
	v_mfma_f32_16x16x32_bf16 v[54:57], v[162:165], v[180:183], v[54:57]
	v_mfma_f32_16x16x32_bf16 v[38:41], v[162:165], v[188:191], v[38:41]
	v_mfma_f32_16x16x32_bf16 v[38:41], v[158:161], v[184:187], v[38:41]
	v_mfma_f32_16x16x32_bf16 v[30:33], v[166:169], v[184:187], v[30:33]
	v_mfma_f32_16x16x32_bf16 v[30:33], v[170:173], v[188:191], v[30:33]
	v_mfma_f32_16x16x32_bf16 v[14:17], v[170:173], v[196:199], v[14:17]
	v_mfma_f32_16x16x32_bf16 v[14:17], v[166:169], v[192:195], v[14:17]
	v_mfma_f32_16x16x32_bf16 v[22:25], v[158:161], v[192:195], v[22:25]
	v_mfma_f32_16x16x32_bf16 v[22:25], v[162:165], v[196:199], v[22:25]
	v_mfma_f32_16x16x32_bf16 v[6:9], v[162:165], v[210:213], v[6:9]
	v_mfma_f32_16x16x32_bf16 v[6:9], v[158:161], v[200:203], v[6:9]
	s_barrier
; #define PG8_STAGE(bufoff, gbase, voff) do { _Pragma("unroll") for (int _i = 0; _i < 2; ++_i) \
;         __builtin_amdgcn_global_load_lds((const unsigned*)((const char*)(gbase) + (size_t)_i * qstep + (voff)[0]), (PG8_LAS unsigned*)(lds + (bufoff) + ldsw + _i * 8192), 16, 0, 0); } while (0)
; #define PG8_LDA(dst, b, h) do { _Pragma("unroll") for (int m = 0; m < 4; ++m) _Pragma("unroll") for (int k = 0; k < 2; ++k) dst[m][k] = *(const PG8_LAS bf16x8*)(lds + PG8_SA(b, h) + aoff + m * 2048 + k * 1024); } while (0)
; #define PG8_LDB(dst, b, h) do { _Pragma("unroll") for (int n = 0; n < 2; ++n) _Pragma("unroll") for (int k = 0; k < 2; ++k) dst[n][k] = *(const PG8_LAS bf16x8*)(lds + PG8_SB(b, h) + boff + n * 2048 + k * 1024); } while (0)
; #define PG8_MMA(ai, bj, At, Bt) do { __builtin_amdgcn_s_setprio(1); _Pragma("unroll") for (int m = 0; m < 4; ++m) _Pragma("unroll") for (int n = 0; n < 2; ++n) _Pragma("unroll") for (int k = 0; k < 2; ++k) \
;         acc[ai][bj][m][n] = __builtin_amdgcn_mfma_f32_16x16x32_bf16(Bt[n][k], At[m][k], acc[ai][bj][m][n], 0, 0, 0); __builtin_amdgcn_s_setprio(0); } while (0)
; #define PG8_WAIT_V89() do { if constexpr (SLIVER) PG8_WAIT_V(9); else PG8_WAIT_V(8); } while (0)
; #define PG8_STAGE_S(b, gbase) do { if constexpr (SLIVER) __builtin_amdgcn_global_load_lds((const unsigned*)((const char*)(gbase) + voffS), (PG8_LAS unsigned*)(lds + STAGE_BYTES + (b) * 2048 + wid * 256), 4, 0, 0); } while (0)
; #define PG8_WAIT_L(n) asm volatile("s_waitcnt lgkmcnt(" #n ")" ::: "memory")
; #define PG8_BAR __builtin_amdgcn_s_barrier()
; #define PG8_SCHED __builtin_amdgcn_sched_barrier(0)
; template <class Epi, class Sched, bool ALIGN_EPI = false, bool SP2 = false, bool SLIVER = false>
; __device__ __forceinline__ void gemm_phase(PG8_LAS unsigned char* lds, const Gemm g, const Sched& S, const Epi& E) {
;     ...
;             PG8_LDB(B0, 1, 0); PG8_LDB(B1, 1, 1); PG8_SCHED; PG8_LDA(At, 1, 0); PG8_STAGE(PG8_SA(0, 1), a2 + hstep, voffA); PG8_STAGE_S(0, s2);
;             PG8_WAIT_V89(); PG8_WAIT_L(0); PG8_BAR; PG8_MMA(0, 0, At, B0); PG8_MMA(0, 1, At, B1); PG8_BAR; PG8_SCHED;
	s_setprio 0
	s_add_i32 s62, 0, 0x18000
	v_add_u32_e32 v144, s62, v145
	s_add_i32 s63, 0, 0x1c000
	ds_read_b128 v[136:139], v144
	ds_read_b128 v[140:143], v144 offset:1024
	ds_read_b128 v[150:153], v144 offset:2048
	ds_read_b128 v[154:157], v144 offset:3072
	v_add_u32_e32 v144, s63, v145
	ds_read_b128 v[158:161], v144
	ds_read_b128 v[162:165], v144 offset:1024
	ds_read_b128 v[166:169], v144 offset:2048
	ds_read_b128 v[170:173], v144 offset:3072
	s_mov_b32 m0, s51
	ds_read_b128 v[174:177], v149 offset:32768
	ds_read_b128 v[180:183], v149 offset:33792
	ds_read_b128 v[184:187], v149 offset:34816
	ds_read_b128 v[188:191], v149 offset:35840
	ds_read_b128 v[192:195], v149 offset:36864
	ds_read_b128 v[196:199], v149 offset:37888
	ds_read_b128 v[200:203], v149 offset:38912
	ds_read_b128 v[210:213], v149 offset:39936
	s_add_u32 s60, s46, 0x80000
	s_addc_u32 s61, s47, 0
	global_load_lds_dwordx4 v130, s[60:61]
	s_mov_b32 m0, s54
	s_nop 0
	s_add_u32 s36, s46, 0xc0000
	s_addc_u32 s37, s47, 0
	global_load_lds_dwordx4 v130, s[36:37]
	s_waitcnt vmcnt(8)
	s_waitcnt lgkmcnt(0)
	s_setprio 1
	s_barrier
	v_mfma_f32_16x16x32_bf16 v[126:129], v[136:139], v[174:177], v[126:129]
	v_mfma_f32_16x16x32_bf16 v[126:129], v[140:143], v[180:183], v[126:129]
	v_mfma_f32_16x16x32_bf16 v[122:125], v[154:157], v[180:183], v[122:125]
	v_mfma_f32_16x16x32_bf16 v[122:125], v[150:153], v[174:177], v[122:125]
	v_mfma_f32_16x16x32_bf16 v[106:109], v[150:153], v[184:187], v[106:109]
	v_mfma_f32_16x16x32_bf16 v[106:109], v[154:157], v[188:191], v[106:109]
	v_mfma_f32_16x16x32_bf16 v[114:117], v[140:143], v[188:191], v[114:117]
	v_mfma_f32_16x16x32_bf16 v[114:117], v[136:139], v[184:187], v[114:117]
	v_mfma_f32_16x16x32_bf16 v[98:101], v[136:139], v[192:195], v[98:101]
	v_mfma_f32_16x16x32_bf16 v[98:101], v[140:143], v[196:199], v[98:101]
	v_mfma_f32_16x16x32_bf16 v[90:93], v[154:157], v[196:199], v[90:93]
	v_mfma_f32_16x16x32_bf16 v[90:93], v[150:153], v[192:195], v[90:93]
	v_mfma_f32_16x16x32_bf16 v[74:77], v[150:153], v[200:203], v[74:77]
	v_mfma_f32_16x16x32_bf16 v[74:77], v[154:157], v[210:213], v[74:77]
	v_mfma_f32_16x16x32_bf16 v[82:85], v[140:143], v[210:213], v[82:85]
	v_mfma_f32_16x16x32_bf16 v[82:85], v[136:139], v[200:203], v[82:85]
	s_setprio 0
	s_setprio 1
	v_mfma_f32_16x16x32_bf16 v[66:69], v[166:169], v[200:203], v[66:69]
	v_mfma_f32_16x16x32_bf16 v[66:69], v[170:173], v[210:213], v[66:69]
	v_mfma_f32_16x16x32_bf16 v[110:113], v[170:173], v[180:183], v[110:113]
	v_mfma_f32_16x16x32_bf16 v[110:113], v[166:169], v[174:177], v[110:113]
	v_mfma_f32_16x16x32_bf16 v[118:121], v[158:161], v[174:177], v[118:121]
	v_mfma_f32_16x16x32_bf16 v[118:121], v[162:165], v[180:183], v[118:121]
	v_mfma_f32_16x16x32_bf16 v[102:105], v[162:165], v[188:191], v[102:105]
	v_mfma_f32_16x16x32_bf16 v[102:105], v[158:161], v[184:187], v[102:105]
	v_mfma_f32_16x16x32_bf16 v[94:97], v[166:169], v[184:187], v[94:97]
	v_mfma_f32_16x16x32_bf16 v[94:97], v[170:173], v[188:191], v[94:97]
	v_mfma_f32_16x16x32_bf16 v[78:81], v[170:173], v[196:199], v[78:81]
	v_mfma_f32_16x16x32_bf16 v[78:81], v[166:169], v[192:195], v[78:81]
	v_mfma_f32_16x16x32_bf16 v[86:89], v[158:161], v[192:195], v[86:89]
	v_mfma_f32_16x16x32_bf16 v[86:89], v[162:165], v[196:199], v[86:89]
	v_mfma_f32_16x16x32_bf16 v[70:73], v[162:165], v[210:213], v[70:73]
	v_mfma_f32_16x16x32_bf16 v[70:73], v[158:161], v[200:203], v[70:73]
	s_barrier
; #define PG8_SB(B) __builtin_amdgcn_rcpf(1.f + expneg(B))
; #define PG8_SB(B) __builtin_amdgcn_rcpf(1.f + expneg(B))
; #define PG8_STAGE(bufoff, gbase, voff) do { _Pragma("unroll") for (int _i = 0; _i < 2; ++_i) \
;         __builtin_amdgcn_global_load_lds((const unsigned*)((const char*)(gbase) + (size_t)_i * qstep + (voff)[0]), (PG8_LAS unsigned*)(lds + (bufoff) + ldsw + _i * 8192), 16, 0, 0); } while (0)
; #define PG8_LDA(dst, b, h) do { _Pragma("unroll") for (int m = 0; m < 4; ++m) _Pragma("unroll") for (int k = 0; k < 2; ++k) dst[m][k] = *(const PG8_LAS bf16x8*)(lds + PG8_SA(b, h) + aoff + m * 2048 + k * 1024); } while (0)
; #define PG8_MMA(ai, bj, At, Bt) do { __builtin_amdgcn_s_setprio(1); _Pragma("unroll") for (int m = 0; m < 4; ++m) _Pragma("unroll") for (int n = 0; n < 2; ++n) _Pragma("unroll") for (int k = 0; k < 2; ++k) \
;         acc[ai][bj][m][n] = __builtin_amdgcn_mfma_f32_16x16x32_bf16(Bt[n][k], At[m][k], acc[ai][bj][m][n], 0, 0, 0); __builtin_amdgcn_s_setprio(0); } while (0)
; #define PG8_WAIT_V89() do { if constexpr (SLIVER) PG8_WAIT_V(9); else PG8_WAIT_V(8); } while (0)
; #define PG8_LDS_S(b) do { if constexpr (SLIVER) { Sf[0] = *(const PG8_LAS bf16x8*)(lds + STAGE_BYTES + (b) * 2048 + soff0); Sf[1] = *(const PG8_LAS bf16x8*)(lds + STAGE_BYTES + (b) * 2048 + (soff0 ^ 64)); } } while (0)
; #define PG8_WAIT_L(n) asm volatile("s_waitcnt lgkmcnt(" #n ")" ::: "memory")
; #define PG8_BAR __builtin_amdgcn_s_barrier()
; #define PG8_SCHED __builtin_amdgcn_sched_barrier(0)
; template <class Epi, class Sched, bool ALIGN_EPI = false, bool SP2 = false, bool SLIVER = false>
; __device__ __forceinline__ void gemm_phase(PG8_LAS unsigned char* lds, const Gemm g, const Sched& S, const Epi& E) {
;     ...
;         for (int t = 0; t < nt; t += 2) {
;             const bool last = (t == nt - 2);
;             const char* a1 = cA + (size_t)(t + 1) * kstep;
;             const char* a2 = last ? nA : cA + (size_t)(t + 2) * kstep; const char* b2 = last ? nB : cB + (size_t)(t + 2) * kstep;
;             const char* a3 = a2 + kstep; const char* b3 = b2 + kstep;
;     ...
;             PG8_LDA(At, 1, 1); PG8_LDS_S(1); PG8_STAGE(PG8_SB(1, 0), b3, voffB); PG8_STAGE(PG8_SB(1, 1), b3 + hstep, voffB); PG8_STAGE(PG8_SA(1, 0), a3, voffA);
;             PG8_WAIT_V89(); PG8_WAIT_L(0); PG8_BAR; PG8_MMA(1, 0, At, B0); PG8_MMA(1, 1, At, B1); PG8_MMA_S(); PG8_BAR; PG8_SCHED;
	s_setprio 0
	s_add_i32 s62, s62, s53
	s_mov_b32 m0, s62
	ds_read_b128 v[174:177], v149 offset:49152
	ds_read_b128 v[180:183], v149 offset:50176
	ds_read_b128 v[184:187], v149 offset:51200
	ds_read_b128 v[188:191], v149 offset:52224
	ds_read_b128 v[192:195], v149 offset:53248
	ds_read_b128 v[196:199], v149 offset:54272
	ds_read_b128 v[200:203], v149 offset:55296
	ds_read_b128 v[210:213], v149 offset:56320
	s_add_u32 s58, s78, 0x80
	s_addc_u32 s59, s79, 0
	global_load_lds_dwordx4 v132, s[58:59]
	s_add_i32 m0, s62, 0x2000
	s_add_i32 s62, s63, s53
	s_add_u32 s60, s78, 0x40080
	s_addc_u32 s61, s79, 0
	global_load_lds_dwordx4 v132, s[60:61]
	s_mov_b32 m0, s62
	s_add_u32 s36, s78, 0x80080
	s_addc_u32 s37, s79, 0
	global_load_lds_dwordx4 v132, s[36:37]
	s_add_i32 m0, s62, 0x2000
	s_nop 0
	s_add_u32 s58, s78, 0xc0080
	s_addc_u32 s59, s79, 0
	global_load_lds_dwordx4 v132, s[58:59]
	s_mov_b32 m0, s10
	s_nop 0
	s_add_u32 s60, s46, 0x80
	s_addc_u32 s61, s47, 0
	global_load_lds_dwordx4 v130, s[60:61]
	s_mov_b32 m0, s55
	s_nop 0
	s_add_u32 s36, s46, 0x40080
	s_addc_u32 s37, s47, 0
	global_load_lds_dwordx4 v130, s[36:37]
	s_waitcnt vmcnt(8)
	s_waitcnt lgkmcnt(0)
	s_setprio 1
	s_barrier
	v_mfma_f32_16x16x32_bf16 v[62:65], v[136:139], v[174:177], v[62:65]
	v_mfma_f32_16x16x32_bf16 v[62:65], v[140:143], v[180:183], v[62:65]
	v_mfma_f32_16x16x32_bf16 v[58:61], v[154:157], v[180:183], v[58:61]
	v_mfma_f32_16x16x32_bf16 v[58:61], v[150:153], v[174:177], v[58:61]
	v_mfma_f32_16x16x32_bf16 v[42:45], v[150:153], v[184:187], v[42:45]
	v_mfma_f32_16x16x32_bf16 v[42:45], v[154:157], v[188:191], v[42:45]
	v_mfma_f32_16x16x32_bf16 v[50:53], v[140:143], v[188:191], v[50:53]
	v_mfma_f32_16x16x32_bf16 v[50:53], v[136:139], v[184:187], v[50:53]
	v_mfma_f32_16x16x32_bf16 v[34:37], v[136:139], v[192:195], v[34:37]
	v_mfma_f32_16x16x32_bf16 v[34:37], v[140:143], v[196:199], v[34:37]
	v_mfma_f32_16x16x32_bf16 v[26:29], v[154:157], v[196:199], v[26:29]
	v_mfma_f32_16x16x32_bf16 v[26:29], v[150:153], v[192:195], v[26:29]
	v_mfma_f32_16x16x32_bf16 v[10:13], v[150:153], v[200:203], v[10:13]
	v_mfma_f32_16x16x32_bf16 v[10:13], v[154:157], v[210:213], v[10:13]
	v_mfma_f32_16x16x32_bf16 v[18:21], v[140:143], v[210:213], v[18:21]
	v_mfma_f32_16x16x32_bf16 v[18:21], v[136:139], v[200:203], v[18:21]
	s_setprio 0
	s_setprio 1
	v_mfma_f32_16x16x32_bf16 v[2:5], v[166:169], v[200:203], v[2:5]
	v_mfma_f32_16x16x32_bf16 v[2:5], v[170:173], v[210:213], v[2:5]
	v_mfma_f32_16x16x32_bf16 v[46:49], v[170:173], v[180:183], v[46:49]
	v_mfma_f32_16x16x32_bf16 v[46:49], v[166:169], v[174:177], v[46:49]
	v_mfma_f32_16x16x32_bf16 v[54:57], v[158:161], v[174:177], v[54:57]
	v_mfma_f32_16x16x32_bf16 v[54:57], v[162:165], v[180:183], v[54:57]
	v_mfma_f32_16x16x32_bf16 v[38:41], v[162:165], v[188:191], v[38:41]
	v_mfma_f32_16x16x32_bf16 v[38:41], v[158:161], v[184:187], v[38:41]
	v_mfma_f32_16x16x32_bf16 v[30:33], v[166:169], v[184:187], v[30:33]
	v_mfma_f32_16x16x32_bf16 v[30:33], v[170:173], v[188:191], v[30:33]
	v_mfma_f32_16x16x32_bf16 v[14:17], v[170:173], v[196:199], v[14:17]
	v_mfma_f32_16x16x32_bf16 v[14:17], v[166:169], v[192:195], v[14:17]
	v_mfma_f32_16x16x32_bf16 v[22:25], v[158:161], v[192:195], v[22:25]
	v_mfma_f32_16x16x32_bf16 v[22:25], v[162:165], v[196:199], v[22:25]
	v_mfma_f32_16x16x32_bf16 v[6:9], v[162:165], v[210:213], v[6:9]
	v_mfma_f32_16x16x32_bf16 v[6:9], v[158:161], v[200:203], v[6:9]
	s_barrier
	s_setprio 0
	s_add_i32 s76, s76, 2
	s_add_u32 s40, s40, 0x100
	s_addc_u32 s41, s41, 0
	s_add_u32 s68, s68, 0x100
	s_addc_u32 s69, s69, 0
	s_cmp_gt_u32 s76, 29
	s_cbranch_scc0 .LBB0_153
	s_and_b64 vcc, exec, s[48:49]
	s_cbranch_vccz .LBB0_156
	s_barrier

; #define PG8_STAGE(bufoff, gbase, voff) do { _Pragma("unroll") for (int _i = 0; _i < 2; ++_i) \
;         __builtin_amdgcn_global_load_lds((const unsigned*)((const char*)(gbase) + (size_t)_i * qstep + (voff)[0]), (PG8_LAS unsigned*)(lds + (bufoff) + ldsw + _i * 8192), 16, 0, 0); } while (0)
; #define PG8_LDA(dst, b, h) do { _Pragma("unroll") for (int m = 0; m < 4; ++m) _Pragma("unroll") for (int k = 0; k < 2; ++k) dst[m][k] = *(const PG8_LAS bf16x8*)(lds + PG8_SA(b, h) + aoff + m * 2048 + k * 1024); } while (0)
; #define PG8_LDB(dst, b, h) do { _Pragma("unroll") for (int n = 0; n < 2; ++n) _Pragma("unroll") for (int k = 0; k < 2; ++k) dst[n][k] = *(const PG8_LAS bf16x8*)(lds + PG8_SB(b, h) + boff + n * 2048 + k * 1024); } while (0)
; #define PG8_WAIT_V89() do { if constexpr (SLIVER) PG8_WAIT_V(9); else PG8_WAIT_V(8); } while (0)
; #define PG8_WAIT_L(n) asm volatile("s_waitcnt lgkmcnt(" #n ")" ::: "memory")
; template <class Epi, class Sched, bool ALIGN_EPI = false, bool SP2 = false, bool SLIVER = false>
; __device__ __forceinline__ void gemm_phase(PG8_LAS unsigned char* lds, const Gemm g, const Sched& S, const Epi& E) {
;     ...
;         const bool has_next = S.next(ui + 1, nxt);
;         const char* nA = has_next ? (const char*)g.A + (size_t)nxt.pm * tstep + Epi::k0(nxt.seg) * 2 : cA; const char* nB = has_next ? (const char*)g.Bt + (size_t)nxt.pn * tstep + Epi::k0(nxt.seg) * 2 : cB;
;         const char* nS = has_next ? (const char*)g.A + (size_t)S.srow0 * K * 2 + (size_t)nxt.pm * sstep + Epi::k0(nxt.seg) * 2 : cS;
;         for (int t = 0; t < nt; t += 2) {
;             const bool last = (t == nt - 2);
;             const char* a1 = cA + (size_t)(t + 1) * kstep;
;             const char* a2 = last ? nA : cA + (size_t)(t + 2) * kstep; const char* b2 = last ? nB : cB + (size_t)(t + 2) * kstep;
;             const char* a3 = a2 + kstep; const char* b3 = b2 + kstep;
;             const char* s1 = cS + (size_t)(t + 1) * kstep; const char* s2 = last ? nS : cS + (size_t)(t + 2) * kstep;
;             if (last && has_next) S.a_ready(nxt);
;             if constexpr (SP2) {
;             PG8_LDB(B0, 0, 0); PG8_LDB(B1, 0, 1); PG8_SCHED; PG8_LDA(At, 0, 0); PG8_STAGE(PG8_SA(1, 1), a1 + hstep, voffA); PG8_STAGE_S(1, s1);
;             PG8_WAIT_V89(); PG8_WAIT_L(0); PG8_BAR; PG8_MMA(0, 0, At, B0); PG8_MMA(0, 1, At, B1); PG8_BAR; PG8_SCHED;
.LBB0_498:
	s_cmp_eq_u32 s66, s80
	s_cselect_b64 s[86:87], -1, 0
	s_add_u32 s40, s16, s80
	s_addc_u32 s41, s17, s81
	s_add_u32 s68, s40, 0x100
	s_addc_u32 s69, s41, 0
	s_and_b64 s[40:41], s[86:87], exec
	s_cselect_b32 s41, s55, s69
	s_cselect_b32 s40, s54, s68
	s_add_u32 s76, s12, s80
	s_addc_u32 s77, s13, s81
	s_add_i32 s78, 0, 0x10000
	s_and_b64 s[68:69], s[86:87], exec
	v_add_u32_e32 v138, s78, v239
	s_cselect_b32 s69, s83, s77
	s_cselect_b32 s68, s82, s76
	s_add_i32 s76, 0, 0x14000
	ds_read_b128 v[146:149], v138
	ds_read_b128 v[150:153], v138 offset:1024
	ds_read_b128 v[154:157], v138 offset:2048
	ds_read_b128 v[158:161], v138 offset:3072
	v_add_u32_e32 v138, s76, v239
	ds_read_b128 v[166:169], v138
	ds_read_b128 v[170:173], v138 offset:1024
	ds_read_b128 v[174:177], v138 offset:2048
	ds_read_b128 v[162:165], v138 offset:3072
	v_lshl_add_u64 v[208:209], v[188:189], 0, s[80:81]
	v_lshl_add_u64 v[224:225], v[208:209], 0, s[34:35]
	s_add_i32 m0, s96, 0xc000
	s_mov_b64 s[88:89], 0x120080
	ds_read_b128 v[138:141], v242
	ds_read_b128 v[142:145], v242 offset:1024
	ds_read_b128 v[180:183], v242 offset:2048
	ds_read_b128 v[184:187], v242 offset:3072
	ds_read_b128 v[192:195], v242 offset:4096
	ds_read_b128 v[196:199], v242 offset:5120
	ds_read_b128 v[200:203], v242 offset:6144
	ds_read_b128 v[220:223], v242 offset:7168
	global_load_lds_dwordx4 v[224:225], off
	v_lshl_add_u64 v[208:209], v[208:209], 0, s[88:89]
	s_add_i32 m0, s96, 0xe000
	s_nop 0
	global_load_lds_dwordx4 v[208:209], off
	v_lshl_add_u64 v[208:209], v[190:191], 0, s[80:81]
	s_add_i32 m0, s94, 0x20800
	s_nop 0
	global_load_lds_dword v[208:209], off
	s_waitcnt vmcnt(9)
	s_waitcnt lgkmcnt(0)
	s_setprio 1
	s_barrier
	v_mfma_f32_16x16x32_bf16 v[134:137], v[146:149], v[138:141], v[134:137]
	v_mfma_f32_16x16x32_bf16 v[134:137], v[150:153], v[142:145], v[134:137]
	v_mfma_f32_16x16x32_bf16 v[130:133], v[158:161], v[142:145], v[130:133]
	v_mfma_f32_16x16x32_bf16 v[130:133], v[154:157], v[138:141], v[130:133]
	v_mfma_f32_16x16x32_bf16 v[122:125], v[154:157], v[180:183], v[122:125]
	v_mfma_f32_16x16x32_bf16 v[122:125], v[158:161], v[184:187], v[122:125]
	v_mfma_f32_16x16x32_bf16 v[126:129], v[150:153], v[184:187], v[126:129]
	v_mfma_f32_16x16x32_bf16 v[126:129], v[146:149], v[180:183], v[126:129]
	v_mfma_f32_16x16x32_bf16 v[118:121], v[146:149], v[192:195], v[118:121]
	v_mfma_f32_16x16x32_bf16 v[118:121], v[150:153], v[196:199], v[118:121]
	v_mfma_f32_16x16x32_bf16 v[114:117], v[158:161], v[196:199], v[114:117]
	v_mfma_f32_16x16x32_bf16 v[114:117], v[154:157], v[192:195], v[114:117]
	v_mfma_f32_16x16x32_bf16 v[106:109], v[154:157], v[200:203], v[106:109]
	v_mfma_f32_16x16x32_bf16 v[106:109], v[158:161], v[220:223], v[106:109]
	v_mfma_f32_16x16x32_bf16 v[110:113], v[150:153], v[220:223], v[110:113]
	v_mfma_f32_16x16x32_bf16 v[110:113], v[146:149], v[200:203], v[110:113]
	s_setprio 0
	s_setprio 1
	v_mfma_f32_16x16x32_bf16 v[66:69], v[174:177], v[200:203], v[66:69]
	v_mfma_f32_16x16x32_bf16 v[66:69], v[162:165], v[220:223], v[66:69]
	v_mfma_f32_16x16x32_bf16 v[98:101], v[162:165], v[142:145], v[98:101]
	v_mfma_f32_16x16x32_bf16 v[98:101], v[174:177], v[138:141], v[98:101]
	v_mfma_f32_16x16x32_bf16 v[102:105], v[166:169], v[138:141], v[102:105]
	v_mfma_f32_16x16x32_bf16 v[102:105], v[170:173], v[142:145], v[102:105]
	v_mfma_f32_16x16x32_bf16 v[90:93], v[170:173], v[184:187], v[90:93]
	v_mfma_f32_16x16x32_bf16 v[90:93], v[166:169], v[180:183], v[90:93]
	v_mfma_f32_16x16x32_bf16 v[86:89], v[174:177], v[180:183], v[86:89]
	v_mfma_f32_16x16x32_bf16 v[86:89], v[162:165], v[184:187], v[86:89]
	v_mfma_f32_16x16x32_bf16 v[74:77], v[162:165], v[196:199], v[74:77]
	v_mfma_f32_16x16x32_bf16 v[74:77], v[174:177], v[192:195], v[74:77]
	v_mfma_f32_16x16x32_bf16 v[78:81], v[166:169], v[192:195], v[78:81]
	v_mfma_f32_16x16x32_bf16 v[78:81], v[170:173], v[196:199], v[78:81]
	v_mfma_f32_16x16x32_bf16 v[70:73], v[170:173], v[220:223], v[70:73]
	v_mfma_f32_16x16x32_bf16 v[70:73], v[166:169], v[200:203], v[70:73]
	s_barrier
; #define PG8_SB(B) __builtin_amdgcn_rcpf(1.f + expneg(B))
; #define PG8_SB(B) __builtin_amdgcn_rcpf(1.f + expneg(B))
; #define PG8_STAGE(bufoff, gbase, voff) do { _Pragma("unroll") for (int _i = 0; _i < 2; ++_i) \
;         __builtin_amdgcn_global_load_lds((const unsigned*)((const char*)(gbase) + (size_t)_i * qstep + (voff)[0]), (PG8_LAS unsigned*)(lds + (bufoff) + ldsw + _i * 8192), 16, 0, 0); } while (0)
; #define PG8_LDA(dst, b, h) do { _Pragma("unroll") for (int m = 0; m < 4; ++m) _Pragma("unroll") for (int k = 0; k < 2; ++k) dst[m][k] = *(const PG8_LAS bf16x8*)(lds + PG8_SA(b, h) + aoff + m * 2048 + k * 1024); } while (0)
; #define PG8_MMA(ai, bj, At, Bt) do { __builtin_amdgcn_s_setprio(1); _Pragma("unroll") for (int m = 0; m < 4; ++m) _Pragma("unroll") for (int n = 0; n < 2; ++n) _Pragma("unroll") for (int k = 0; k < 2; ++k) \
;         acc[ai][bj][m][n] = __builtin_amdgcn_mfma_f32_16x16x32_bf16(Bt[n][k], At[m][k], acc[ai][bj][m][n], 0, 0, 0); __builtin_amdgcn_s_setprio(0); } while (0)
; #define PG8_WAIT_V89() do { if constexpr (SLIVER) PG8_WAIT_V(9); else PG8_WAIT_V(8); } while (0)
; #define PG8_LDS_S(b) do { if constexpr (SLIVER) { Sf[0] = *(const PG8_LAS bf16x8*)(lds + STAGE_BYTES + (b) * 2048 + soff0); Sf[1] = *(const PG8_LAS bf16x8*)(lds + STAGE_BYTES + (b) * 2048 + (soff0 ^ 64)); } } while (0)
; #define PG8_WAIT_L(n) asm volatile("s_waitcnt lgkmcnt(" #n ")" ::: "memory")
; #define PG8_BAR __builtin_amdgcn_s_barrier()
; #define PG8_SCHED __builtin_amdgcn_sched_barrier(0)
; template <class Epi, class Sched, bool ALIGN_EPI = false, bool SP2 = false, bool SLIVER = false>
; __device__ __forceinline__ void gemm_phase(PG8_LAS unsigned char* lds, const Gemm g, const Sched& S, const Epi& E) {
;     ...
;             PG8_LDA(At, 0, 1); PG8_LDS_S(0); PG8_STAGE(PG8_SB(0, 0), b2, voffB); PG8_STAGE(PG8_SB(0, 1), b2 + hstep, voffB); PG8_STAGE(PG8_SA(0, 0), a2, voffA);
;             PG8_WAIT_V89(); PG8_WAIT_L(0); PG8_BAR; PG8_MMA(1, 0, At, B0); PG8_MMA(1, 1, At, B1); PG8_MMA_S(); PG8_BAR; PG8_SCHED;
	s_setprio 0
	s_add_i32 s77, 0, 0x20000
	v_lshl_add_u64 v[192:193], s[68:69], 0, v[212:213]
	s_add_i32 s68, s78, s95
	v_add_u32_e32 v178, s77, v240
	v_add_u32_e32 v184, s77, v241
	s_mov_b32 m0, s68
	s_mov_b64 s[88:89], 0x60000
	ds_read_b128 v[138:141], v242 offset:16384
	ds_read_b128 v[142:145], v242 offset:17408
	ds_read_b128 v[196:199], v242 offset:18432
	ds_read_b128 v[200:203], v242 offset:19456
	ds_read_b128 v[220:223], v242 offset:20480
	ds_read_b128 v[224:227], v242 offset:21504
	ds_read_b128 v[228:231], v242 offset:22528
	ds_read_b128 v[232:235], v242 offset:23552
	ds_read_b128 v[180:183], v178
	ds_read_b128 v[184:187], v184
	global_load_lds_dwordx4 v[192:193], off
	v_lshl_add_u64 v[194:195], v[192:193], 0, s[88:89]
	s_add_i32 m0, s68, 0x2000
	s_add_i32 s68, s76, s95
	global_load_lds_dwordx4 v[194:195], off
	v_lshl_add_u64 v[194:195], v[192:193], 0, s[24:25]
	s_mov_b32 m0, s68
	s_nop 0
	global_load_lds_dwordx4 v[194:195], off
	v_lshl_add_u64 v[194:195], v[192:193], 0, s[14:15]
	s_add_i32 m0, s68, 0x2000
	s_nop 0
	global_load_lds_dwordx4 v[194:195], off
	v_lshl_add_u64 v[194:195], s[40:41], 0, v[210:211]
	s_mov_b32 m0, s96
	v_lshl_add_u64 v[208:209], v[194:195], 0, s[88:89]
	global_load_lds_dwordx4 v[194:195], off
	s_mov_b32 m0, s19
	s_nop 0
	global_load_lds_dwordx4 v[208:209], off
	s_waitcnt vmcnt(9)
	s_waitcnt lgkmcnt(0)
	s_setprio 1
	s_barrier
	v_mfma_f32_16x16x32_bf16 v[62:65], v[146:149], v[138:141], v[62:65]
	v_mfma_f32_16x16x32_bf16 v[62:65], v[150:153], v[142:145], v[62:65]
	v_mfma_f32_16x16x32_bf16 v[58:61], v[158:161], v[142:145], v[58:61]
	v_mfma_f32_16x16x32_bf16 v[58:61], v[154:157], v[138:141], v[58:61]
	v_mfma_f32_16x16x32_bf16 v[50:53], v[154:157], v[196:199], v[50:53]
	v_mfma_f32_16x16x32_bf16 v[50:53], v[158:161], v[200:203], v[50:53]
	v_mfma_f32_16x16x32_bf16 v[54:57], v[150:153], v[200:203], v[54:57]
	v_mfma_f32_16x16x32_bf16 v[54:57], v[146:149], v[196:199], v[54:57]
	v_mfma_f32_16x16x32_bf16 v[46:49], v[146:149], v[220:223], v[46:49]
	v_mfma_f32_16x16x32_bf16 v[46:49], v[150:153], v[224:227], v[46:49]
	v_mfma_f32_16x16x32_bf16 v[42:45], v[158:161], v[224:227], v[42:45]
	v_mfma_f32_16x16x32_bf16 v[42:45], v[154:157], v[220:223], v[42:45]
	v_mfma_f32_16x16x32_bf16 v[34:37], v[154:157], v[228:231], v[34:37]
	v_mfma_f32_16x16x32_bf16 v[34:37], v[158:161], v[232:235], v[34:37]
	v_mfma_f32_16x16x32_bf16 v[38:41], v[150:153], v[232:235], v[38:41]
	v_mfma_f32_16x16x32_bf16 v[38:41], v[146:149], v[228:231], v[38:41]
	s_setprio 0
	s_setprio 1
	v_mfma_f32_16x16x32_bf16 v[2:5], v[174:177], v[228:231], v[2:5]
	v_mfma_f32_16x16x32_bf16 v[2:5], v[162:165], v[232:235], v[2:5]
	v_mfma_f32_16x16x32_bf16 v[26:29], v[162:165], v[142:145], v[26:29]
	v_mfma_f32_16x16x32_bf16 v[26:29], v[174:177], v[138:141], v[26:29]
	v_mfma_f32_16x16x32_bf16 v[30:33], v[166:169], v[138:141], v[30:33]
	v_mfma_f32_16x16x32_bf16 v[30:33], v[170:173], v[142:145], v[30:33]
	v_mfma_f32_16x16x32_bf16 v[22:25], v[170:173], v[200:203], v[22:25]
	v_mfma_f32_16x16x32_bf16 v[22:25], v[166:169], v[196:199], v[22:25]
	v_mfma_f32_16x16x32_bf16 v[18:21], v[174:177], v[196:199], v[18:21]
	v_mfma_f32_16x16x32_bf16 v[18:21], v[162:165], v[200:203], v[18:21]
	v_mfma_f32_16x16x32_bf16 v[10:13], v[162:165], v[224:227], v[10:13]
	v_mfma_f32_16x16x32_bf16 v[10:13], v[174:177], v[220:223], v[10:13]
	v_mfma_f32_16x16x32_bf16 v[14:17], v[166:169], v[220:223], v[14:17]
	v_mfma_f32_16x16x32_bf16 v[14:17], v[170:173], v[224:227], v[14:17]
	v_mfma_f32_16x16x32_bf16 v[6:9], v[170:173], v[232:235], v[6:9]
	v_mfma_f32_16x16x32_bf16 v[6:9], v[166:169], v[228:231], v[6:9]
	s_setprio 0
	s_setprio 1
	s_and_b64 vcc, exec, s[52:53]
	s_cbranch_vccz .Lslv_b0
	v_mfma_f32_16x16x32_bf16 v[138:141], v[166:169], v[180:183], v[82:85]
	v_mfma_f32_16x16x32_bf16 v[142:145], v[174:177], v[180:183], v[94:97]
	v_mfma_f32_16x16x32_bf16 v[138:141], v[170:173], v[184:187], v[138:141]
	v_mfma_f32_16x16x32_bf16 v[142:145], v[162:165], v[184:187], v[142:145]
	s_branch .LBB0_502

; #define PG8_STAGE(bufoff, gbase, voff) do { _Pragma("unroll") for (int _i = 0; _i < 2; ++_i) \
;         __builtin_amdgcn_global_load_lds((const unsigned*)((const char*)(gbase) + (size_t)_i * qstep + (voff)[0]), (PG8_LAS unsigned*)(lds + (bufoff) + ldsw + _i * 8192), 16, 0, 0); } while (0)
; #define PG8_LDA(dst, b, h) do { _Pragma("unroll") for (int m = 0; m < 4; ++m) _Pragma("unroll") for (int k = 0; k < 2; ++k) dst[m][k] = *(const PG8_LAS bf16x8*)(lds + PG8_SA(b, h) + aoff + m * 2048 + k * 1024); } while (0)
; #define PG8_LDB(dst, b, h) do { _Pragma("unroll") for (int n = 0; n < 2; ++n) _Pragma("unroll") for (int k = 0; k < 2; ++k) dst[n][k] = *(const PG8_LAS bf16x8*)(lds + PG8_SB(b, h) + boff + n * 2048 + k * 1024); } while (0)
; #define PG8_MMA(ai, bj, At, Bt) do { __builtin_amdgcn_s_setprio(1); _Pragma("unroll") for (int m = 0; m < 4; ++m) _Pragma("unroll") for (int n = 0; n < 2; ++n) _Pragma("unroll") for (int k = 0; k < 2; ++k) \
;         acc[ai][bj][m][n] = __builtin_amdgcn_mfma_f32_16x16x32_bf16(Bt[n][k], At[m][k], acc[ai][bj][m][n], 0, 0, 0); __builtin_amdgcn_s_setprio(0); } while (0)
; #define PG8_WAIT_V89() do { if constexpr (SLIVER) PG8_WAIT_V(9); else PG8_WAIT_V(8); } while (0)
; #define PG8_STAGE_S(b, gbase) do { if constexpr (SLIVER) __builtin_amdgcn_global_load_lds((const unsigned*)((const char*)(gbase) + voffS), (PG8_LAS unsigned*)(lds + STAGE_BYTES + (b) * 2048 + wid * 256), 4, 0, 0); } while (0)
; #define PG8_WAIT_L(n) asm volatile("s_waitcnt lgkmcnt(" #n ")" ::: "memory")
; #define PG8_BAR __builtin_amdgcn_s_barrier()
; #define PG8_SCHED __builtin_amdgcn_sched_barrier(0)
; template <class Epi, class Sched, bool ALIGN_EPI = false, bool SP2 = false, bool SLIVER = false>
; __device__ __forceinline__ void gemm_phase(PG8_LAS unsigned char* lds, const Gemm g, const Sched& S, const Epi& E) {
;     ...
;             PG8_LDB(B0, 1, 0); PG8_LDB(B1, 1, 1); PG8_SCHED; PG8_LDA(At, 1, 0); PG8_STAGE(PG8_SA(0, 1), a2 + hstep, voffA); PG8_STAGE_S(0, s2);
;             PG8_WAIT_V89(); PG8_WAIT_L(0); PG8_BAR; PG8_MMA(0, 0, At, B0); PG8_MMA(0, 1, At, B1); PG8_BAR; PG8_SCHED;
.LBB0_502:
	s_barrier
	s_setprio 0
	s_add_u32 s68, s62, s80
	s_addc_u32 s69, s63, s81
	s_add_u32 s76, s68, 0x100
	s_addc_u32 s77, s69, 0
	s_and_b64 s[68:69], s[86:87], exec
	s_cselect_b32 s69, s85, s77
	s_cselect_b32 s68, s84, s76
	s_add_i32 s76, 0, 0x18000
	v_add_u32_e32 v82, s76, v239
	s_add_i32 s77, 0, 0x1c000
	ds_read_b128 v[146:149], v82
	ds_read_b128 v[150:153], v82 offset:1024
	ds_read_b128 v[154:157], v82 offset:2048
	ds_read_b128 v[158:161], v82 offset:3072
	v_add_u32_e32 v82, s77, v239
	ds_read_b128 v[166:169], v82
	ds_read_b128 v[170:173], v82 offset:1024
	ds_read_b128 v[174:177], v82 offset:2048
	ds_read_b128 v[162:165], v82 offset:3072
	s_mov_b32 m0, s91
	v_lshl_add_u64 v[208:209], v[194:195], 0, s[24:25]
	ds_read_b128 v[82:85], v242 offset:32768
	ds_read_b128 v[94:97], v242 offset:33792
	ds_read_b128 v[180:183], v242 offset:34816
	ds_read_b128 v[184:187], v242 offset:35840
	ds_read_b128 v[196:199], v242 offset:36864
	ds_read_b128 v[200:203], v242 offset:37888
	ds_read_b128 v[220:223], v242 offset:38912
	ds_read_b128 v[224:227], v242 offset:39936
	global_load_lds_dwordx4 v[208:209], off
	v_lshl_add_u64 v[208:209], v[194:195], 0, s[14:15]
	s_mov_b32 m0, s92
	s_nop 0
	global_load_lds_dwordx4 v[208:209], off
	v_lshl_add_u64 v[208:209], s[68:69], 0, v[214:215]
	s_mov_b32 m0, s93
	s_nop 0
	global_load_lds_dword v[208:209], off
	s_waitcnt vmcnt(9)
	s_waitcnt lgkmcnt(0)
	s_setprio 1
	s_barrier
	v_mfma_f32_16x16x32_bf16 v[134:137], v[146:149], v[82:85], v[134:137]
	v_mfma_f32_16x16x32_bf16 v[134:137], v[150:153], v[94:97], v[134:137]
	v_mfma_f32_16x16x32_bf16 v[130:133], v[158:161], v[94:97], v[130:133]
	v_mfma_f32_16x16x32_bf16 v[130:133], v[154:157], v[82:85], v[130:133]
	v_mfma_f32_16x16x32_bf16 v[122:125], v[154:157], v[180:183], v[122:125]
	v_mfma_f32_16x16x32_bf16 v[122:125], v[158:161], v[184:187], v[122:125]
	v_mfma_f32_16x16x32_bf16 v[126:129], v[150:153], v[184:187], v[126:129]
	v_mfma_f32_16x16x32_bf16 v[126:129], v[146:149], v[180:183], v[126:129]
	v_mfma_f32_16x16x32_bf16 v[118:121], v[146:149], v[196:199], v[118:121]
	v_mfma_f32_16x16x32_bf16 v[118:121], v[150:153], v[200:203], v[118:121]
	v_mfma_f32_16x16x32_bf16 v[114:117], v[158:161], v[200:203], v[114:117]
	v_mfma_f32_16x16x32_bf16 v[114:117], v[154:157], v[196:199], v[114:117]
	v_mfma_f32_16x16x32_bf16 v[106:109], v[154:157], v[220:223], v[106:109]
	v_mfma_f32_16x16x32_bf16 v[106:109], v[158:161], v[224:227], v[106:109]
	v_mfma_f32_16x16x32_bf16 v[110:113], v[150:153], v[224:227], v[110:113]
	v_mfma_f32_16x16x32_bf16 v[110:113], v[146:149], v[220:223], v[110:113]
	s_setprio 0
	s_setprio 1
	v_mfma_f32_16x16x32_bf16 v[102:105], v[166:169], v[82:85], v[102:105]
	v_mfma_f32_16x16x32_bf16 v[102:105], v[170:173], v[94:97], v[102:105]
	v_mfma_f32_16x16x32_bf16 v[82:85], v[174:177], v[82:85], v[98:101]
	v_mfma_f32_16x16x32_bf16 v[98:101], v[162:165], v[94:97], v[82:85]
	v_mfma_f32_16x16x32_bf16 v[82:85], v[166:169], v[180:183], v[90:93]
	v_mfma_f32_16x16x32_bf16 v[90:93], v[170:173], v[184:187], v[82:85]
	v_mfma_f32_16x16x32_bf16 v[82:85], v[174:177], v[180:183], v[86:89]
	v_mfma_f32_16x16x32_bf16 v[86:89], v[162:165], v[184:187], v[82:85]
	v_mfma_f32_16x16x32_bf16 v[78:81], v[166:169], v[196:199], v[78:81]
	v_mfma_f32_16x16x32_bf16 v[78:81], v[170:173], v[200:203], v[78:81]
	v_mfma_f32_16x16x32_bf16 v[74:77], v[174:177], v[196:199], v[74:77]
	v_mfma_f32_16x16x32_bf16 v[74:77], v[162:165], v[200:203], v[74:77]
	v_mfma_f32_16x16x32_bf16 v[70:73], v[166:169], v[220:223], v[70:73]
	v_mfma_f32_16x16x32_bf16 v[70:73], v[170:173], v[224:227], v[70:73]
	v_mfma_f32_16x16x32_bf16 v[66:69], v[174:177], v[220:223], v[66:69]
	v_mfma_f32_16x16x32_bf16 v[66:69], v[162:165], v[224:227], v[66:69]
	s_barrier
; #define PG8_SB(B) __builtin_amdgcn_rcpf(1.f + expneg(B))
; #define PG8_SB(B) __builtin_amdgcn_rcpf(1.f + expneg(B))
; #define PG8_STAGE(bufoff, gbase, voff) do { _Pragma("unroll") for (int _i = 0; _i < 2; ++_i) \
;         __builtin_amdgcn_global_load_lds((const unsigned*)((const char*)(gbase) + (size_t)_i * qstep + (voff)[0]), (PG8_LAS unsigned*)(lds + (bufoff) + ldsw + _i * 8192), 16, 0, 0); } while (0)
; #define PG8_LDA(dst, b, h) do { _Pragma("unroll") for (int m = 0; m < 4; ++m) _Pragma("unroll") for (int k = 0; k < 2; ++k) dst[m][k] = *(const PG8_LAS bf16x8*)(lds + PG8_SA(b, h) + aoff + m * 2048 + k * 1024); } while (0)
; #define PG8_MMA(ai, bj, At, Bt) do { __builtin_amdgcn_s_setprio(1); _Pragma("unroll") for (int m = 0; m < 4; ++m) _Pragma("unroll") for (int n = 0; n < 2; ++n) _Pragma("unroll") for (int k = 0; k < 2; ++k) \
;         acc[ai][bj][m][n] = __builtin_amdgcn_mfma_f32_16x16x32_bf16(Bt[n][k], At[m][k], acc[ai][bj][m][n], 0, 0, 0); __builtin_amdgcn_s_setprio(0); } while (0)
; #define PG8_WAIT_V89() do { if constexpr (SLIVER) PG8_WAIT_V(9); else PG8_WAIT_V(8); } while (0)
; #define PG8_LDS_S(b) do { if constexpr (SLIVER) { Sf[0] = *(const PG8_LAS bf16x8*)(lds + STAGE_BYTES + (b) * 2048 + soff0); Sf[1] = *(const PG8_LAS bf16x8*)(lds + STAGE_BYTES + (b) * 2048 + (soff0 ^ 64)); } } while (0)
; #define PG8_WAIT_L(n) asm volatile("s_waitcnt lgkmcnt(" #n ")" ::: "memory")
; #define PG8_BAR __builtin_amdgcn_s_barrier()
; #define PG8_SCHED __builtin_amdgcn_sched_barrier(0)
; template <class Epi, class Sched, bool ALIGN_EPI = false, bool SP2 = false, bool SLIVER = false>
; __device__ __forceinline__ void gemm_phase(PG8_LAS unsigned char* lds, const Gemm g, const Sched& S, const Epi& E) {
;     ...
;             PG8_LDA(At, 1, 1); PG8_LDS_S(1); PG8_STAGE(PG8_SB(1, 0), b3, voffB); PG8_STAGE(PG8_SB(1, 1), b3 + hstep, voffB); PG8_STAGE(PG8_SA(1, 0), a3, voffA);
;             PG8_WAIT_V89(); PG8_WAIT_L(0); PG8_BAR; PG8_MMA(1, 0, At, B0); PG8_MMA(1, 1, At, B1); PG8_MMA_S(); PG8_BAR; PG8_SCHED;
	s_setprio 0
	s_add_i32 s68, 0, 0x20800
	v_add_u32_e32 v178, s68, v240
	v_add_u32_e32 v184, s68, v241
	s_add_i32 s68, s76, s95
	v_lshl_add_u64 v[208:209], v[192:193], 0, s[26:27]
	s_mov_b32 m0, s68
	ds_read_b128 v[82:85], v242 offset:49152
	ds_read_b128 v[94:97], v242 offset:50176
	ds_read_b128 v[196:199], v242 offset:51200
	ds_read_b128 v[200:203], v242 offset:52224
	ds_read_b128 v[220:223], v242 offset:53248
	ds_read_b128 v[224:227], v242 offset:54272
	ds_read_b128 v[228:231], v242 offset:55296
	ds_read_b128 v[232:235], v242 offset:56320
	ds_read_b128 v[180:183], v178
	ds_read_b128 v[184:187], v184
	global_load_lds_dwordx4 v[208:209], off
	v_lshl_add_u64 v[208:209], v[192:193], 0, s[72:73]
	s_add_i32 m0, s68, 0x2000
	s_add_i32 s68, s77, s95
	global_load_lds_dwordx4 v[208:209], off
	v_lshl_add_u64 v[208:209], v[192:193], 0, s[34:35]
	s_mov_b32 m0, s68
	s_mov_b64 s[76:77], 0x120080
	global_load_lds_dwordx4 v[208:209], off
	v_lshl_add_u64 v[192:193], v[192:193], 0, s[76:77]
	s_add_i32 m0, s68, 0x2000
	s_nop 0
	global_load_lds_dwordx4 v[192:193], off
	v_lshl_add_u64 v[192:193], v[194:195], 0, s[26:27]
	s_mov_b32 m0, s97
	s_nop 0
	global_load_lds_dwordx4 v[192:193], off
	v_lshl_add_u64 v[192:193], v[194:195], 0, s[72:73]
	s_mov_b32 m0, s18
	s_nop 0
	global_load_lds_dwordx4 v[192:193], off
	s_waitcnt vmcnt(9)
	s_waitcnt lgkmcnt(0)
	s_setprio 1
	s_barrier
	v_mfma_f32_16x16x32_bf16 v[62:65], v[146:149], v[82:85], v[62:65]
	v_mfma_f32_16x16x32_bf16 v[62:65], v[150:153], v[94:97], v[62:65]
	v_mfma_f32_16x16x32_bf16 v[58:61], v[158:161], v[94:97], v[58:61]
	v_mfma_f32_16x16x32_bf16 v[58:61], v[154:157], v[82:85], v[58:61]
	v_mfma_f32_16x16x32_bf16 v[50:53], v[154:157], v[196:199], v[50:53]
	v_mfma_f32_16x16x32_bf16 v[50:53], v[158:161], v[200:203], v[50:53]
	v_mfma_f32_16x16x32_bf16 v[54:57], v[150:153], v[200:203], v[54:57]
	v_mfma_f32_16x16x32_bf16 v[54:57], v[146:149], v[196:199], v[54:57]
	v_mfma_f32_16x16x32_bf16 v[46:49], v[146:149], v[220:223], v[46:49]
	v_mfma_f32_16x16x32_bf16 v[46:49], v[150:153], v[224:227], v[46:49]
	v_mfma_f32_16x16x32_bf16 v[42:45], v[158:161], v[224:227], v[42:45]
	v_mfma_f32_16x16x32_bf16 v[42:45], v[154:157], v[220:223], v[42:45]
	v_mfma_f32_16x16x32_bf16 v[34:37], v[154:157], v[228:231], v[34:37]
	v_mfma_f32_16x16x32_bf16 v[34:37], v[158:161], v[232:235], v[34:37]
	v_mfma_f32_16x16x32_bf16 v[38:41], v[150:153], v[232:235], v[38:41]
	v_mfma_f32_16x16x32_bf16 v[38:41], v[146:149], v[228:231], v[38:41]
	s_setprio 0
	s_setprio 1
	v_mfma_f32_16x16x32_bf16 v[2:5], v[174:177], v[228:231], v[2:5]
	v_mfma_f32_16x16x32_bf16 v[2:5], v[162:165], v[232:235], v[2:5]
	v_mfma_f32_16x16x32_bf16 v[26:29], v[162:165], v[94:97], v[26:29]
	v_mfma_f32_16x16x32_bf16 v[26:29], v[174:177], v[82:85], v[26:29]
	v_mfma_f32_16x16x32_bf16 v[30:33], v[166:169], v[82:85], v[30:33]
	v_mfma_f32_16x16x32_bf16 v[30:33], v[170:173], v[94:97], v[30:33]
	v_mfma_f32_16x16x32_bf16 v[22:25], v[170:173], v[200:203], v[22:25]
	v_mfma_f32_16x16x32_bf16 v[22:25], v[166:169], v[196:199], v[22:25]
	v_mfma_f32_16x16x32_bf16 v[18:21], v[174:177], v[196:199], v[18:21]
	v_mfma_f32_16x16x32_bf16 v[18:21], v[162:165], v[200:203], v[18:21]
	v_mfma_f32_16x16x32_bf16 v[10:13], v[162:165], v[224:227], v[10:13]
	v_mfma_f32_16x16x32_bf16 v[10:13], v[174:177], v[220:223], v[10:13]
	v_mfma_f32_16x16x32_bf16 v[14:17], v[166:169], v[220:223], v[14:17]
	v_mfma_f32_16x16x32_bf16 v[14:17], v[170:173], v[224:227], v[14:17]
	v_mfma_f32_16x16x32_bf16 v[6:9], v[170:173], v[232:235], v[6:9]
	v_mfma_f32_16x16x32_bf16 v[6:9], v[166:169], v[228:231], v[6:9]
	s_setprio 0
	s_setprio 1
	s_and_b64 vcc, exec, s[52:53]
	s_cbranch_vccz .Lslv_c0
	v_mfma_f32_16x16x32_bf16 v[82:85], v[166:169], v[180:183], v[138:141]
	v_mfma_f32_16x16x32_bf16 v[94:97], v[174:177], v[180:183], v[142:145]
	v_mfma_f32_16x16x32_bf16 v[82:85], v[170:173], v[184:187], v[82:85]
	v_mfma_f32_16x16x32_bf16 v[94:97], v[162:165], v[184:187], v[94:97]
	s_branch .LBB0_497

; #define PG8_STAGE(bufoff, gbase, voff) do { _Pragma("unroll") for (int _i = 0; _i < 2; ++_i) \
;         __builtin_amdgcn_global_load_lds((const unsigned*)((const char*)(gbase) + (size_t)_i * qstep + (voff)[0]), (PG8_LAS unsigned*)(lds + (bufoff) + ldsw + _i * 8192), 16, 0, 0); } while (0)
; #define PG8_LDA(dst, b, h) do { _Pragma("unroll") for (int m = 0; m < 4; ++m) _Pragma("unroll") for (int k = 0; k < 2; ++k) dst[m][k] = *(const PG8_LAS bf16x8*)(lds + PG8_SA(b, h) + aoff + m * 2048 + k * 1024); } while (0)
; #define PG8_LDB(dst, b, h) do { _Pragma("unroll") for (int n = 0; n < 2; ++n) _Pragma("unroll") for (int k = 0; k < 2; ++k) dst[n][k] = *(const PG8_LAS bf16x8*)(lds + PG8_SB(b, h) + boff + n * 2048 + k * 1024); } while (0)
; #define PG8_WAIT_V89() do { if constexpr (SLIVER) PG8_WAIT_V(9); else PG8_WAIT_V(8); } while (0)
; #define PG8_WAIT_L(n) asm volatile("s_waitcnt lgkmcnt(" #n ")" ::: "memory")
; template <class Epi, class Sched, bool ALIGN_EPI = false, bool SP2 = false, bool SLIVER = false>
; __device__ __forceinline__ void gemm_phase(PG8_LAS unsigned char* lds, const Gemm g, const Sched& S, const Epi& E) {
;     ...
;         const bool has_next = S.next(ui + 1, nxt);
;         const char* nA = has_next ? (const char*)g.A + (size_t)nxt.pm * tstep + Epi::k0(nxt.seg) * 2 : cA; const char* nB = has_next ? (const char*)g.Bt + (size_t)nxt.pn * tstep + Epi::k0(nxt.seg) * 2 : cB;
;         const char* nS = has_next ? (const char*)g.A + (size_t)S.srow0 * K * 2 + (size_t)nxt.pm * sstep + Epi::k0(nxt.seg) * 2 : cS;
;         for (int t = 0; t < nt; t += 2) {
;             const bool last = (t == nt - 2);
;             const char* a1 = cA + (size_t)(t + 1) * kstep;
;             const char* a2 = last ? nA : cA + (size_t)(t + 2) * kstep; const char* b2 = last ? nB : cB + (size_t)(t + 2) * kstep;
;             const char* a3 = a2 + kstep; const char* b3 = b2 + kstep;
;             const char* s1 = cS + (size_t)(t + 1) * kstep; const char* s2 = last ? nS : cS + (size_t)(t + 2) * kstep;
;             if (last && has_next) S.a_ready(nxt);
;             if constexpr (SP2) {
;             PG8_LDB(B0, 0, 0); PG8_LDB(B1, 0, 1); PG8_SCHED; PG8_LDA(At, 0, 0); PG8_STAGE(PG8_SA(1, 1), a1 + hstep, voffA); PG8_STAGE_S(1, s1);
;             PG8_WAIT_V89(); PG8_WAIT_L(0); PG8_BAR; PG8_MMA(0, 0, At, B0); PG8_MMA(0, 1, At, B1); PG8_BAR; PG8_SCHED;
.LBB0_598:
	s_add_u32 s40, s92, s62
	s_addc_u32 s41, s93, s63
	s_add_u32 s77, s40, 0x100
	s_addc_u32 s78, s41, 0
	s_add_u32 s83, s68, s62
	s_addc_u32 s79, s69, s63
	s_add_i32 s96, 0, 0x10000
	s_cmpk_eq_i32 s62, 0xf00
	s_cselect_b64 s[80:81], -1, 0
	s_and_b64 s[40:41], s[80:81], exec
	s_cselect_b32 s41, s12, s78
	s_cselect_b32 s40, s13, s77
	v_add_u32_e32 v138, s96, v212
	s_cselect_b32 s79, s17, s79
	s_cselect_b32 s78, s55, s83
	s_add_i32 s77, 0, 0x14000
	ds_read_b128 v[146:149], v138
	ds_read_b128 v[150:153], v138 offset:1024
	ds_read_b128 v[154:157], v138 offset:2048
	ds_read_b128 v[158:161], v138 offset:3072
	v_add_u32_e32 v138, s77, v212
	ds_read_b128 v[166:169], v138
	ds_read_b128 v[170:173], v138 offset:1024
	ds_read_b128 v[174:177], v138 offset:2048
	ds_read_b128 v[162:165], v138 offset:3072
	v_lshl_add_u64 v[202:203], v[200:201], 0, s[62:63]
	v_lshl_add_u64 v[208:209], v[202:203], 0, s[30:31]
	s_add_i32 m0, s85, 0xc000
	ds_read_b128 v[138:141], v215
	ds_read_b128 v[142:145], v215 offset:1024
	ds_read_b128 v[180:183], v215 offset:2048
	ds_read_b128 v[184:187], v215 offset:3072
	ds_read_b128 v[216:219], v215 offset:4096
	ds_read_b128 v[220:223], v215 offset:5120
	ds_read_b128 v[224:227], v215 offset:6144
	ds_read_b128 v[228:231], v215 offset:7168
	global_load_lds_dwordx4 v[208:209], off
	v_lshl_add_u64 v[202:203], v[202:203], 0, s[34:35]
	s_add_i32 m0, s85, 0xe000
	s_nop 0
	global_load_lds_dwordx4 v[202:203], off
	v_lshl_add_u64 v[202:203], v[198:199], 0, s[62:63]
	s_add_i32 m0, s45, 0x20800
	s_nop 0
	global_load_lds_dword v[202:203], off
	s_waitcnt vmcnt(9)
	s_waitcnt lgkmcnt(0)
	s_setprio 1
	s_barrier
	v_mfma_f32_16x16x32_bf16 v[134:137], v[146:149], v[138:141], v[134:137]
	v_mfma_f32_16x16x32_bf16 v[134:137], v[150:153], v[142:145], v[134:137]
	v_mfma_f32_16x16x32_bf16 v[130:133], v[158:161], v[142:145], v[130:133]
	v_mfma_f32_16x16x32_bf16 v[130:133], v[154:157], v[138:141], v[130:133]
	v_mfma_f32_16x16x32_bf16 v[114:117], v[154:157], v[180:183], v[114:117]
	v_mfma_f32_16x16x32_bf16 v[114:117], v[158:161], v[184:187], v[114:117]
	v_mfma_f32_16x16x32_bf16 v[118:121], v[150:153], v[184:187], v[118:121]
	v_mfma_f32_16x16x32_bf16 v[118:121], v[146:149], v[180:183], v[118:121]
	v_mfma_f32_16x16x32_bf16 v[102:105], v[146:149], v[216:219], v[102:105]
	v_mfma_f32_16x16x32_bf16 v[102:105], v[150:153], v[220:223], v[102:105]
	v_mfma_f32_16x16x32_bf16 v[98:101], v[158:161], v[220:223], v[98:101]
	v_mfma_f32_16x16x32_bf16 v[98:101], v[154:157], v[216:219], v[98:101]
	v_mfma_f32_16x16x32_bf16 v[82:85], v[154:157], v[224:227], v[82:85]
	v_mfma_f32_16x16x32_bf16 v[82:85], v[158:161], v[228:231], v[82:85]
	v_mfma_f32_16x16x32_bf16 v[86:89], v[150:153], v[228:231], v[86:89]
	v_mfma_f32_16x16x32_bf16 v[86:89], v[146:149], v[224:227], v[86:89]
	s_setprio 0
	s_setprio 1
	v_mfma_f32_16x16x32_bf16 v[74:77], v[174:177], v[224:227], v[74:77]
	v_mfma_f32_16x16x32_bf16 v[74:77], v[162:165], v[228:231], v[74:77]
	v_mfma_f32_16x16x32_bf16 v[122:125], v[162:165], v[142:145], v[122:125]
	v_mfma_f32_16x16x32_bf16 v[122:125], v[174:177], v[138:141], v[122:125]
	v_mfma_f32_16x16x32_bf16 v[126:129], v[166:169], v[138:141], v[126:129]
	v_mfma_f32_16x16x32_bf16 v[126:129], v[170:173], v[142:145], v[126:129]
	v_mfma_f32_16x16x32_bf16 v[110:113], v[170:173], v[184:187], v[110:113]
	v_mfma_f32_16x16x32_bf16 v[110:113], v[166:169], v[180:183], v[110:113]
	v_mfma_f32_16x16x32_bf16 v[106:109], v[174:177], v[180:183], v[106:109]
	v_mfma_f32_16x16x32_bf16 v[106:109], v[162:165], v[184:187], v[106:109]
	v_mfma_f32_16x16x32_bf16 v[90:93], v[162:165], v[220:223], v[90:93]
	v_mfma_f32_16x16x32_bf16 v[90:93], v[174:177], v[216:219], v[90:93]
	v_mfma_f32_16x16x32_bf16 v[94:97], v[166:169], v[216:219], v[94:97]
	v_mfma_f32_16x16x32_bf16 v[94:97], v[170:173], v[220:223], v[94:97]
	v_mfma_f32_16x16x32_bf16 v[78:81], v[170:173], v[228:231], v[78:81]
	v_mfma_f32_16x16x32_bf16 v[78:81], v[166:169], v[224:227], v[78:81]
	s_barrier
; #define PG8_SB(B) __builtin_amdgcn_rcpf(1.f + expneg(B))
; #define PG8_SB(B) __builtin_amdgcn_rcpf(1.f + expneg(B))
; #define PG8_STAGE(bufoff, gbase, voff) do { _Pragma("unroll") for (int _i = 0; _i < 2; ++_i) \
;         __builtin_amdgcn_global_load_lds((const unsigned*)((const char*)(gbase) + (size_t)_i * qstep + (voff)[0]), (PG8_LAS unsigned*)(lds + (bufoff) + ldsw + _i * 8192), 16, 0, 0); } while (0)
; #define PG8_LDA(dst, b, h) do { _Pragma("unroll") for (int m = 0; m < 4; ++m) _Pragma("unroll") for (int k = 0; k < 2; ++k) dst[m][k] = *(const PG8_LAS bf16x8*)(lds + PG8_SA(b, h) + aoff + m * 2048 + k * 1024); } while (0)
; #define PG8_MMA(ai, bj, At, Bt) do { __builtin_amdgcn_s_setprio(1); _Pragma("unroll") for (int m = 0; m < 4; ++m) _Pragma("unroll") for (int n = 0; n < 2; ++n) _Pragma("unroll") for (int k = 0; k < 2; ++k) \
;         acc[ai][bj][m][n] = __builtin_amdgcn_mfma_f32_16x16x32_bf16(Bt[n][k], At[m][k], acc[ai][bj][m][n], 0, 0, 0); __builtin_amdgcn_s_setprio(0); } while (0)
; #define PG8_WAIT_V89() do { if constexpr (SLIVER) PG8_WAIT_V(9); else PG8_WAIT_V(8); } while (0)
; #define PG8_LDS_S(b) do { if constexpr (SLIVER) { Sf[0] = *(const PG8_LAS bf16x8*)(lds + STAGE_BYTES + (b) * 2048 + soff0); Sf[1] = *(const PG8_LAS bf16x8*)(lds + STAGE_BYTES + (b) * 2048 + (soff0 ^ 64)); } } while (0)
; #define PG8_WAIT_L(n) asm volatile("s_waitcnt lgkmcnt(" #n ")" ::: "memory")
; #define PG8_BAR __builtin_amdgcn_s_barrier()
; #define PG8_SCHED __builtin_amdgcn_sched_barrier(0)
; template <class Epi, class Sched, bool ALIGN_EPI = false, bool SP2 = false, bool SLIVER = false>
; __device__ __forceinline__ void gemm_phase(PG8_LAS unsigned char* lds, const Gemm g, const Sched& S, const Epi& E) {
;     ...
;             PG8_LDA(At, 0, 1); PG8_LDS_S(0); PG8_STAGE(PG8_SB(0, 0), b2, voffB); PG8_STAGE(PG8_SB(0, 1), b2 + hstep, voffB); PG8_STAGE(PG8_SA(0, 0), a2, voffA);
;             PG8_WAIT_V89(); PG8_WAIT_L(0); PG8_BAR; PG8_MMA(1, 0, At, B0); PG8_MMA(1, 1, At, B1); PG8_MMA_S(); PG8_BAR; PG8_SCHED;
	s_setprio 0
	s_add_i32 s83, 0, 0x20000
	v_lshl_add_u64 v[202:203], s[78:79], 0, v[190:191]
	s_add_i32 s78, s96, s18
	v_add_u32_e32 v178, s83, v213
	v_add_u32_e32 v184, s83, v214
	s_mov_b32 m0, s78
	ds_read_b128 v[138:141], v215 offset:16384
	ds_read_b128 v[142:145], v215 offset:17408
	ds_read_b128 v[216:219], v215 offset:18432
	ds_read_b128 v[220:223], v215 offset:19456
	ds_read_b128 v[224:227], v215 offset:20480
	ds_read_b128 v[228:231], v215 offset:21504
	ds_read_b128 v[232:235], v215 offset:22528
	ds_read_b128 v[240:243], v215 offset:23552
	ds_read_b128 v[180:183], v178
	ds_read_b128 v[184:187], v184
	global_load_lds_dwordx4 v[202:203], off
	v_lshl_add_u64 v[208:209], v[202:203], 0, s[20:21]
	s_add_i32 m0, s78, 0x2000
	s_add_i32 s77, s77, s18
	global_load_lds_dwordx4 v[208:209], off
	v_lshl_add_u64 v[208:209], v[202:203], 0, s[22:23]
	s_mov_b32 m0, s77
	v_lshl_add_u64 v[210:211], s[40:41], 0, v[188:189]
	global_load_lds_dwordx4 v[208:209], off
	v_lshl_add_u64 v[208:209], v[202:203], 0, s[24:25]
	s_add_i32 m0, s77, 0x2000
	s_nop 0
	global_load_lds_dwordx4 v[208:209], off
	s_mov_b32 m0, s85
	v_lshl_add_u64 v[208:209], v[210:211], 0, s[20:21]
	global_load_lds_dwordx4 v[210:211], off
	s_mov_b32 m0, s19
	s_nop 0
	global_load_lds_dwordx4 v[208:209], off
	s_waitcnt vmcnt(9)
	s_waitcnt lgkmcnt(0)
	s_setprio 1
	s_barrier
	v_mfma_f32_16x16x32_bf16 v[70:73], v[146:149], v[138:141], v[70:73]
	v_mfma_f32_16x16x32_bf16 v[70:73], v[150:153], v[142:145], v[70:73]
	v_mfma_f32_16x16x32_bf16 v[66:69], v[158:161], v[142:145], v[66:69]
	v_mfma_f32_16x16x32_bf16 v[66:69], v[154:157], v[138:141], v[66:69]
	v_mfma_f32_16x16x32_bf16 v[50:53], v[154:157], v[216:219], v[50:53]
	v_mfma_f32_16x16x32_bf16 v[50:53], v[158:161], v[220:223], v[50:53]
	v_mfma_f32_16x16x32_bf16 v[54:57], v[150:153], v[220:223], v[54:57]
	v_mfma_f32_16x16x32_bf16 v[54:57], v[146:149], v[216:219], v[54:57]
	v_mfma_f32_16x16x32_bf16 v[38:41], v[146:149], v[224:227], v[38:41]
	v_mfma_f32_16x16x32_bf16 v[38:41], v[150:153], v[228:231], v[38:41]
	v_mfma_f32_16x16x32_bf16 v[34:37], v[158:161], v[228:231], v[34:37]
	v_mfma_f32_16x16x32_bf16 v[34:37], v[154:157], v[224:227], v[34:37]
	v_mfma_f32_16x16x32_bf16 v[18:21], v[154:157], v[232:235], v[18:21]
	v_mfma_f32_16x16x32_bf16 v[18:21], v[158:161], v[240:243], v[18:21]
	v_mfma_f32_16x16x32_bf16 v[22:25], v[150:153], v[240:243], v[22:25]
	v_mfma_f32_16x16x32_bf16 v[22:25], v[146:149], v[232:235], v[22:25]
	s_setprio 0
	s_setprio 1
	v_mfma_f32_16x16x32_bf16 v[10:13], v[174:177], v[232:235], v[10:13]
	v_mfma_f32_16x16x32_bf16 v[10:13], v[162:165], v[240:243], v[10:13]
	v_mfma_f32_16x16x32_bf16 v[58:61], v[162:165], v[142:145], v[58:61]
	v_mfma_f32_16x16x32_bf16 v[58:61], v[174:177], v[138:141], v[58:61]
	v_mfma_f32_16x16x32_bf16 v[62:65], v[166:169], v[138:141], v[62:65]
	v_mfma_f32_16x16x32_bf16 v[62:65], v[170:173], v[142:145], v[62:65]
	v_mfma_f32_16x16x32_bf16 v[46:49], v[170:173], v[220:223], v[46:49]
	v_mfma_f32_16x16x32_bf16 v[46:49], v[166:169], v[216:219], v[46:49]
	v_mfma_f32_16x16x32_bf16 v[42:45], v[174:177], v[216:219], v[42:45]
	v_mfma_f32_16x16x32_bf16 v[42:45], v[162:165], v[220:223], v[42:45]
	v_mfma_f32_16x16x32_bf16 v[26:29], v[162:165], v[228:231], v[26:29]
	v_mfma_f32_16x16x32_bf16 v[26:29], v[174:177], v[224:227], v[26:29]
	v_mfma_f32_16x16x32_bf16 v[30:33], v[166:169], v[224:227], v[30:33]
	v_mfma_f32_16x16x32_bf16 v[30:33], v[170:173], v[228:231], v[30:33]
	v_mfma_f32_16x16x32_bf16 v[14:17], v[170:173], v[240:243], v[14:17]
	v_mfma_f32_16x16x32_bf16 v[14:17], v[166:169], v[232:235], v[14:17]
	s_setprio 0
	s_setprio 1
	s_and_b64 vcc, exec, s[52:53]
	s_cbranch_vccz .Lslv_b1
	v_mfma_f32_16x16x32_bf16 v[138:141], v[166:169], v[180:183], v[6:9]
	v_mfma_f32_16x16x32_bf16 v[142:145], v[174:177], v[180:183], v[2:5]
	v_mfma_f32_16x16x32_bf16 v[138:141], v[170:173], v[184:187], v[138:141]
	v_mfma_f32_16x16x32_bf16 v[142:145], v[162:165], v[184:187], v[142:145]
	s_branch .LBB0_602

; #define PG8_SB(B) __builtin_amdgcn_rcpf(1.f + expneg(B))
; #define PG8_SB(B) __builtin_amdgcn_rcpf(1.f + expneg(B))
; #define PG8_STAGE(bufoff, gbase, voff) do { _Pragma("unroll") for (int _i = 0; _i < 2; ++_i) \
;         __builtin_amdgcn_global_load_lds((const unsigned*)((const char*)(gbase) + (size_t)_i * qstep + (voff)[0]), (PG8_LAS unsigned*)(lds + (bufoff) + ldsw + _i * 8192), 16, 0, 0); } while (0)
; #define PG8_LDA(dst, b, h) do { _Pragma("unroll") for (int m = 0; m < 4; ++m) _Pragma("unroll") for (int k = 0; k < 2; ++k) dst[m][k] = *(const PG8_LAS bf16x8*)(lds + PG8_SA(b, h) + aoff + m * 2048 + k * 1024); } while (0)
; #define PG8_LDB(dst, b, h) do { _Pragma("unroll") for (int n = 0; n < 2; ++n) _Pragma("unroll") for (int k = 0; k < 2; ++k) dst[n][k] = *(const PG8_LAS bf16x8*)(lds + PG8_SB(b, h) + boff + n * 2048 + k * 1024); } while (0)
; #define PG8_MMA(ai, bj, At, Bt) do { __builtin_amdgcn_s_setprio(1); _Pragma("unroll") for (int m = 0; m < 4; ++m) _Pragma("unroll") for (int n = 0; n < 2; ++n) _Pragma("unroll") for (int k = 0; k < 2; ++k) \
;         acc[ai][bj][m][n] = __builtin_amdgcn_mfma_f32_16x16x32_bf16(Bt[n][k], At[m][k], acc[ai][bj][m][n], 0, 0, 0); __builtin_amdgcn_s_setprio(0); } while (0)
; #define PG8_WAIT_V89() do { if constexpr (SLIVER) PG8_WAIT_V(9); else PG8_WAIT_V(8); } while (0)
; #define PG8_STAGE_S(b, gbase) do { if constexpr (SLIVER) __builtin_amdgcn_global_load_lds((const unsigned*)((const char*)(gbase) + voffS), (PG8_LAS unsigned*)(lds + STAGE_BYTES + (b) * 2048 + wid * 256), 4, 0, 0); } while (0)
; #define PG8_BAR __builtin_amdgcn_s_barrier()
; template <class Epi, class Sched, bool ALIGN_EPI = false, bool SP2 = false, bool SLIVER = false>
; __device__ __forceinline__ void gemm_phase(PG8_LAS unsigned char* lds, const Gemm g, const Sched& S, const Epi& E) {
;     ...
;             PG8_LDB(B0, 0, 0); PG8_LDB(B1, 0, 1); PG8_SCHED; PG8_LDA(At, 0, 0); PG8_STAGE(PG8_SA(1, 1), a1 + hstep, voffA); PG8_STAGE_S(1, s1);
;             PG8_WAIT_V89(); PG8_WAIT_L(0); PG8_BAR; PG8_MMA(0, 0, At, B0); PG8_MMA(0, 1, At, B1); PG8_BAR; PG8_SCHED;
;             PG8_LDA(At, 0, 1); PG8_LDS_S(0); PG8_STAGE(PG8_SB(0, 0), b2, voffB); PG8_STAGE(PG8_SB(0, 1), b2 + hstep, voffB); PG8_STAGE(PG8_SA(0, 0), a2, voffA);
;             PG8_WAIT_V89(); PG8_WAIT_L(0); PG8_BAR; PG8_MMA(1, 0, At, B0); PG8_MMA(1, 1, At, B1); PG8_MMA_S(); PG8_BAR; PG8_SCHED;
.Lgup_skipw0:
	s_waitcnt lgkmcnt(0)
	s_setprio 1
	s_barrier
	v_mfma_f32_16x16x32_bf16 v[126:129], v[130:133], v[172:175], v[126:129]
	v_mfma_f32_16x16x32_bf16 v[126:129], v[138:141], v[180:183], v[126:129]
	v_mfma_f32_16x16x32_bf16 v[118:121], v[152:155], v[180:183], v[118:121]
	v_mfma_f32_16x16x32_bf16 v[118:121], v[148:151], v[172:175], v[118:121]
	v_mfma_f32_16x16x32_bf16 v[102:105], v[148:151], v[184:187], v[102:105]
	v_mfma_f32_16x16x32_bf16 v[102:105], v[152:155], v[188:191], v[102:105]
	v_mfma_f32_16x16x32_bf16 v[110:113], v[138:141], v[188:191], v[110:113]
	v_mfma_f32_16x16x32_bf16 v[110:113], v[130:133], v[184:187], v[110:113]
	v_mfma_f32_16x16x32_bf16 v[94:97], v[130:133], v[192:195], v[94:97]
	v_mfma_f32_16x16x32_bf16 v[94:97], v[138:141], v[196:199], v[94:97]
	v_mfma_f32_16x16x32_bf16 v[86:89], v[152:155], v[196:199], v[86:89]
	v_mfma_f32_16x16x32_bf16 v[86:89], v[148:151], v[192:195], v[86:89]
	v_mfma_f32_16x16x32_bf16 v[70:73], v[148:151], v[200:203], v[70:73]
	v_mfma_f32_16x16x32_bf16 v[70:73], v[152:155], v[210:213], v[70:73]
	v_mfma_f32_16x16x32_bf16 v[78:81], v[138:141], v[210:213], v[78:81]
	v_mfma_f32_16x16x32_bf16 v[78:81], v[130:133], v[200:203], v[78:81]
	s_setprio 0
	s_setprio 1
	v_mfma_f32_16x16x32_bf16 v[66:69], v[164:167], v[200:203], v[66:69]
	v_mfma_f32_16x16x32_bf16 v[66:69], v[168:171], v[210:213], v[66:69]
	v_mfma_f32_16x16x32_bf16 v[114:117], v[168:171], v[180:183], v[114:117]
	v_mfma_f32_16x16x32_bf16 v[114:117], v[164:167], v[172:175], v[114:117]
	v_mfma_f32_16x16x32_bf16 v[122:125], v[156:159], v[172:175], v[122:125]
	v_mfma_f32_16x16x32_bf16 v[122:125], v[160:163], v[180:183], v[122:125]
	v_mfma_f32_16x16x32_bf16 v[106:109], v[160:163], v[188:191], v[106:109]
	v_mfma_f32_16x16x32_bf16 v[106:109], v[156:159], v[184:187], v[106:109]
	v_mfma_f32_16x16x32_bf16 v[98:101], v[164:167], v[184:187], v[98:101]
	v_mfma_f32_16x16x32_bf16 v[98:101], v[168:171], v[188:191], v[98:101]
	v_mfma_f32_16x16x32_bf16 v[82:85], v[168:171], v[196:199], v[82:85]
	v_mfma_f32_16x16x32_bf16 v[82:85], v[164:167], v[192:195], v[82:85]
	v_mfma_f32_16x16x32_bf16 v[90:93], v[156:159], v[192:195], v[90:93]
	v_mfma_f32_16x16x32_bf16 v[90:93], v[160:163], v[196:199], v[90:93]
	v_mfma_f32_16x16x32_bf16 v[74:77], v[160:163], v[210:213], v[74:77]
	v_mfma_f32_16x16x32_bf16 v[74:77], v[156:159], v[200:203], v[74:77]
	s_barrier
	s_setprio 0
	s_mov_b64 s[46:47], s[76:77]
	s_add_i32 s76, s78, s88
	s_mov_b32 m0, s76
	ds_read_b128 v[172:175], v147 offset:16384
	ds_read_b128 v[180:183], v147 offset:17408
	ds_read_b128 v[184:187], v147 offset:18432
	ds_read_b128 v[188:191], v147 offset:19456
	ds_read_b128 v[192:195], v147 offset:20480
	ds_read_b128 v[196:199], v147 offset:21504
	ds_read_b128 v[200:203], v147 offset:22528
	ds_read_b128 v[210:213], v147 offset:23552
	global_load_lds_dwordx4 v178, s[46:47]
	s_add_i32 m0, s76, 0x2000
	s_add_i32 s76, s79, s88
	s_add_u32 s58, s46, 0x40000
	s_addc_u32 s59, s47, 0
	global_load_lds_dwordx4 v178, s[58:59]
	s_mov_b32 m0, s76
	s_nop 0
	s_add_u32 s60, s46, 0x80000
	s_addc_u32 s61, s47, 0
	global_load_lds_dwordx4 v178, s[60:61]
	s_add_i32 m0, s76, 0x2000
	s_nop 0
	s_add_u32 s36, s46, 0xc0000
	s_addc_u32 s37, s47, 0
	global_load_lds_dwordx4 v178, s[36:37]
	s_mov_b32 m0, s45
	s_nop 0
	global_load_lds_dwordx4 v134, s[80:81]
	s_mov_b32 m0, s83
	s_nop 0
	s_add_u32 s58, s80, 0x40000
	s_addc_u32 s59, s81, 0
	global_load_lds_dwordx4 v134, s[58:59]
	s_cmp_eq_u32 s69, s101
	s_cbranch_scc1 .Lgup_skipw1
	s_waitcnt vmcnt(8)
.Lgup_skipw1:
	s_waitcnt lgkmcnt(0)
	s_setprio 1
	s_barrier
	v_mfma_f32_16x16x32_bf16 v[62:65], v[130:133], v[172:175], v[62:65]
	v_mfma_f32_16x16x32_bf16 v[62:65], v[138:141], v[180:183], v[62:65]
	v_mfma_f32_16x16x32_bf16 v[54:57], v[152:155], v[180:183], v[54:57]
	v_mfma_f32_16x16x32_bf16 v[54:57], v[148:151], v[172:175], v[54:57]
	v_mfma_f32_16x16x32_bf16 v[38:41], v[148:151], v[184:187], v[38:41]
	v_mfma_f32_16x16x32_bf16 v[38:41], v[152:155], v[188:191], v[38:41]
	v_mfma_f32_16x16x32_bf16 v[46:49], v[138:141], v[188:191], v[46:49]
	v_mfma_f32_16x16x32_bf16 v[46:49], v[130:133], v[184:187], v[46:49]
	v_mfma_f32_16x16x32_bf16 v[30:33], v[130:133], v[192:195], v[30:33]
	v_mfma_f32_16x16x32_bf16 v[30:33], v[138:141], v[196:199], v[30:33]
	v_mfma_f32_16x16x32_bf16 v[22:25], v[152:155], v[196:199], v[22:25]
	v_mfma_f32_16x16x32_bf16 v[22:25], v[148:151], v[192:195], v[22:25]
	v_mfma_f32_16x16x32_bf16 v[6:9], v[148:151], v[200:203], v[6:9]
	v_mfma_f32_16x16x32_bf16 v[6:9], v[152:155], v[210:213], v[6:9]
	v_mfma_f32_16x16x32_bf16 v[14:17], v[138:141], v[210:213], v[14:17]
	v_mfma_f32_16x16x32_bf16 v[14:17], v[130:133], v[200:203], v[14:17]
	s_setprio 0
	s_setprio 1
	v_mfma_f32_16x16x32_bf16 v[2:5], v[164:167], v[200:203], v[2:5]
	v_mfma_f32_16x16x32_bf16 v[2:5], v[168:171], v[210:213], v[2:5]
	v_mfma_f32_16x16x32_bf16 v[50:53], v[168:171], v[180:183], v[50:53]
	v_mfma_f32_16x16x32_bf16 v[50:53], v[164:167], v[172:175], v[50:53]
	v_mfma_f32_16x16x32_bf16 v[58:61], v[156:159], v[172:175], v[58:61]
	v_mfma_f32_16x16x32_bf16 v[58:61], v[160:163], v[180:183], v[58:61]
	v_mfma_f32_16x16x32_bf16 v[42:45], v[160:163], v[188:191], v[42:45]
	v_mfma_f32_16x16x32_bf16 v[42:45], v[156:159], v[184:187], v[42:45]
	v_mfma_f32_16x16x32_bf16 v[34:37], v[164:167], v[184:187], v[34:37]
	v_mfma_f32_16x16x32_bf16 v[34:37], v[168:171], v[188:191], v[34:37]
	v_mfma_f32_16x16x32_bf16 v[18:21], v[168:171], v[196:199], v[18:21]
	v_mfma_f32_16x16x32_bf16 v[18:21], v[164:167], v[192:195], v[18:21]
	v_mfma_f32_16x16x32_bf16 v[26:29], v[156:159], v[192:195], v[26:29]
	v_mfma_f32_16x16x32_bf16 v[26:29], v[160:163], v[196:199], v[26:29]
	v_mfma_f32_16x16x32_bf16 v[10:13], v[160:163], v[210:213], v[10:13]
	v_mfma_f32_16x16x32_bf16 v[10:13], v[156:159], v[200:203], v[10:13]
	s_barrier
; #define PG8_STAGE(bufoff, gbase, voff) do { _Pragma("unroll") for (int _i = 0; _i < 2; ++_i) \
;         __builtin_amdgcn_global_load_lds((const unsigned*)((const char*)(gbase) + (size_t)_i * qstep + (voff)[0]), (PG8_LAS unsigned*)(lds + (bufoff) + ldsw + _i * 8192), 16, 0, 0); } while (0)
; #define PG8_LDA(dst, b, h) do { _Pragma("unroll") for (int m = 0; m < 4; ++m) _Pragma("unroll") for (int k = 0; k < 2; ++k) dst[m][k] = *(const PG8_LAS bf16x8*)(lds + PG8_SA(b, h) + aoff + m * 2048 + k * 1024); } while (0)
; #define PG8_LDB(dst, b, h) do { _Pragma("unroll") for (int n = 0; n < 2; ++n) _Pragma("unroll") for (int k = 0; k < 2; ++k) dst[n][k] = *(const PG8_LAS bf16x8*)(lds + PG8_SB(b, h) + boff + n * 2048 + k * 1024); } while (0)
; #define PG8_MMA(ai, bj, At, Bt) do { __builtin_amdgcn_s_setprio(1); _Pragma("unroll") for (int m = 0; m < 4; ++m) _Pragma("unroll") for (int n = 0; n < 2; ++n) _Pragma("unroll") for (int k = 0; k < 2; ++k) \
;         acc[ai][bj][m][n] = __builtin_amdgcn_mfma_f32_16x16x32_bf16(Bt[n][k], At[m][k], acc[ai][bj][m][n], 0, 0, 0); __builtin_amdgcn_s_setprio(0); } while (0)
; #define PG8_WAIT_V89() do { if constexpr (SLIVER) PG8_WAIT_V(9); else PG8_WAIT_V(8); } while (0)
; #define PG8_STAGE_S(b, gbase) do { if constexpr (SLIVER) __builtin_amdgcn_global_load_lds((const unsigned*)((const char*)(gbase) + voffS), (PG8_LAS unsigned*)(lds + STAGE_BYTES + (b) * 2048 + wid * 256), 4, 0, 0); } while (0)
; #define PG8_WAIT_L(n) asm volatile("s_waitcnt lgkmcnt(" #n ")" ::: "memory")
; #define PG8_BAR __builtin_amdgcn_s_barrier()
; #define PG8_SCHED __builtin_amdgcn_sched_barrier(0)
; template <class Epi, class Sched, bool ALIGN_EPI = false, bool SP2 = false, bool SLIVER = false>
; __device__ __forceinline__ void gemm_phase(PG8_LAS unsigned char* lds, const Gemm g, const Sched& S, const Epi& E) {
;     ...
;             PG8_LDB(B0, 1, 0); PG8_LDB(B1, 1, 1); PG8_SCHED; PG8_LDA(At, 1, 0); PG8_STAGE(PG8_SA(0, 1), a2 + hstep, voffA); PG8_STAGE_S(0, s2);
;             PG8_WAIT_V89(); PG8_WAIT_L(0); PG8_BAR; PG8_MMA(0, 0, At, B0); PG8_MMA(0, 1, At, B1); PG8_BAR; PG8_SCHED;
	s_setprio 0
	s_add_i32 s76, 0, 0x18000
	v_add_u32_e32 v142, s76, v143
	s_add_i32 s77, 0, 0x1c000
	ds_read_b128 v[130:133], v142
	ds_read_b128 v[138:141], v142 offset:1024
	ds_read_b128 v[148:151], v142 offset:2048
	ds_read_b128 v[152:155], v142 offset:3072
	v_add_u32_e32 v142, s77, v143
	ds_read_b128 v[156:159], v142
	ds_read_b128 v[160:163], v142 offset:1024
	ds_read_b128 v[164:167], v142 offset:2048
	ds_read_b128 v[168:171], v142 offset:3072
	s_mov_b32 m0, s90
	ds_read_b128 v[172:175], v147 offset:32768
	ds_read_b128 v[180:183], v147 offset:33792
	ds_read_b128 v[184:187], v147 offset:34816
	ds_read_b128 v[188:191], v147 offset:35840
	ds_read_b128 v[192:195], v147 offset:36864
	ds_read_b128 v[196:199], v147 offset:37888
	ds_read_b128 v[200:203], v147 offset:38912
	ds_read_b128 v[210:213], v147 offset:39936
	s_add_u32 s60, s80, 0x80000
	s_addc_u32 s61, s81, 0
	global_load_lds_dwordx4 v134, s[60:61]
	s_mov_b32 m0, s91
	s_nop 0
	s_add_u32 s36, s80, 0xc0000
	s_addc_u32 s37, s81, 0
	global_load_lds_dwordx4 v134, s[36:37]
	s_waitcnt vmcnt(8)
	s_waitcnt lgkmcnt(0)
	s_setprio 1
	s_barrier
	v_mfma_f32_16x16x32_bf16 v[126:129], v[130:133], v[172:175], v[126:129]
	v_mfma_f32_16x16x32_bf16 v[126:129], v[138:141], v[180:183], v[126:129]
	v_mfma_f32_16x16x32_bf16 v[118:121], v[152:155], v[180:183], v[118:121]
	v_mfma_f32_16x16x32_bf16 v[118:121], v[148:151], v[172:175], v[118:121]
	v_mfma_f32_16x16x32_bf16 v[102:105], v[148:151], v[184:187], v[102:105]
	v_mfma_f32_16x16x32_bf16 v[102:105], v[152:155], v[188:191], v[102:105]
	v_mfma_f32_16x16x32_bf16 v[110:113], v[138:141], v[188:191], v[110:113]
	v_mfma_f32_16x16x32_bf16 v[110:113], v[130:133], v[184:187], v[110:113]
	v_mfma_f32_16x16x32_bf16 v[94:97], v[130:133], v[192:195], v[94:97]
	v_mfma_f32_16x16x32_bf16 v[94:97], v[138:141], v[196:199], v[94:97]
	v_mfma_f32_16x16x32_bf16 v[86:89], v[152:155], v[196:199], v[86:89]
	v_mfma_f32_16x16x32_bf16 v[86:89], v[148:151], v[192:195], v[86:89]
	v_mfma_f32_16x16x32_bf16 v[70:73], v[148:151], v[200:203], v[70:73]
	v_mfma_f32_16x16x32_bf16 v[70:73], v[152:155], v[210:213], v[70:73]
	v_mfma_f32_16x16x32_bf16 v[78:81], v[138:141], v[210:213], v[78:81]
	v_mfma_f32_16x16x32_bf16 v[78:81], v[130:133], v[200:203], v[78:81]
	s_setprio 0
	s_setprio 1
	v_mfma_f32_16x16x32_bf16 v[66:69], v[164:167], v[200:203], v[66:69]
	v_mfma_f32_16x16x32_bf16 v[66:69], v[168:171], v[210:213], v[66:69]
	v_mfma_f32_16x16x32_bf16 v[114:117], v[168:171], v[180:183], v[114:117]
	v_mfma_f32_16x16x32_bf16 v[114:117], v[164:167], v[172:175], v[114:117]
	v_mfma_f32_16x16x32_bf16 v[122:125], v[156:159], v[172:175], v[122:125]
	v_mfma_f32_16x16x32_bf16 v[122:125], v[160:163], v[180:183], v[122:125]
	v_mfma_f32_16x16x32_bf16 v[106:109], v[160:163], v[188:191], v[106:109]
	v_mfma_f32_16x16x32_bf16 v[106:109], v[156:159], v[184:187], v[106:109]
	v_mfma_f32_16x16x32_bf16 v[98:101], v[164:167], v[184:187], v[98:101]
	v_mfma_f32_16x16x32_bf16 v[98:101], v[168:171], v[188:191], v[98:101]
	v_mfma_f32_16x16x32_bf16 v[82:85], v[168:171], v[196:199], v[82:85]
	v_mfma_f32_16x16x32_bf16 v[82:85], v[164:167], v[192:195], v[82:85]
	v_mfma_f32_16x16x32_bf16 v[90:93], v[156:159], v[192:195], v[90:93]
	v_mfma_f32_16x16x32_bf16 v[90:93], v[160:163], v[196:199], v[90:93]
	v_mfma_f32_16x16x32_bf16 v[74:77], v[160:163], v[210:213], v[74:77]
	v_mfma_f32_16x16x32_bf16 v[74:77], v[156:159], v[200:203], v[74:77]
	s_barrier
; #define PG8_SB(B) __builtin_amdgcn_rcpf(1.f + expneg(B))
; #define PG8_SB(B) __builtin_amdgcn_rcpf(1.f + expneg(B))
; #define PG8_STAGE(bufoff, gbase, voff) do { _Pragma("unroll") for (int _i = 0; _i < 2; ++_i) \
;         __builtin_amdgcn_global_load_lds((const unsigned*)((const char*)(gbase) + (size_t)_i * qstep + (voff)[0]), (PG8_LAS unsigned*)(lds + (bufoff) + ldsw + _i * 8192), 16, 0, 0); } while (0)
; #define PG8_LDA(dst, b, h) do { _Pragma("unroll") for (int m = 0; m < 4; ++m) _Pragma("unroll") for (int k = 0; k < 2; ++k) dst[m][k] = *(const PG8_LAS bf16x8*)(lds + PG8_SA(b, h) + aoff + m * 2048 + k * 1024); } while (0)
; #define PG8_LDB(dst, b, h) do { _Pragma("unroll") for (int n = 0; n < 2; ++n) _Pragma("unroll") for (int k = 0; k < 2; ++k) dst[n][k] = *(const PG8_LAS bf16x8*)(lds + PG8_SB(b, h) + boff + n * 2048 + k * 1024); } while (0)
; #define PG8_MMA(ai, bj, At, Bt) do { __builtin_amdgcn_s_setprio(1); _Pragma("unroll") for (int m = 0; m < 4; ++m) _Pragma("unroll") for (int n = 0; n < 2; ++n) _Pragma("unroll") for (int k = 0; k < 2; ++k) \
;         acc[ai][bj][m][n] = __builtin_amdgcn_mfma_f32_16x16x32_bf16(Bt[n][k], At[m][k], acc[ai][bj][m][n], 0, 0, 0); __builtin_amdgcn_s_setprio(0); } while (0)
; #define PG8_WAIT_V89() do { if constexpr (SLIVER) PG8_WAIT_V(9); else PG8_WAIT_V(8); } while (0)
; #define PG8_STAGE_S(b, gbase) do { if constexpr (SLIVER) __builtin_amdgcn_global_load_lds((const unsigned*)((const char*)(gbase) + voffS), (PG8_LAS unsigned*)(lds + STAGE_BYTES + (b) * 2048 + wid * 256), 4, 0, 0); } while (0)
; template <class Epi, class Sched, bool ALIGN_EPI = false, bool SP2 = false, bool SLIVER = false>
; __device__ __forceinline__ void gemm_phase(PG8_LAS unsigned char* lds, const Gemm g, const Sched& S, const Epi& E) {
;     ...
;         for (int t = 0; t < nt; t += 2) {
;     ...
;             PG8_LDB(B0, 1, 0); PG8_LDB(B1, 1, 1); PG8_SCHED; PG8_LDA(At, 1, 0); PG8_STAGE(PG8_SA(0, 1), a2 + hstep, voffA); PG8_STAGE_S(0, s2);
;             PG8_WAIT_V89(); PG8_WAIT_L(0); PG8_BAR; PG8_MMA(0, 0, At, B0); PG8_MMA(0, 1, At, B1); PG8_BAR; PG8_SCHED;
;             PG8_LDA(At, 1, 1); PG8_LDS_S(1); PG8_STAGE(PG8_SB(1, 0), b3, voffB); PG8_STAGE(PG8_SB(1, 1), b3 + hstep, voffB); PG8_STAGE(PG8_SA(1, 0), a3, voffA);
;             PG8_WAIT_V89(); PG8_WAIT_L(0); PG8_BAR; PG8_MMA(1, 0, At, B0); PG8_MMA(1, 1, At, B1); PG8_MMA_S(); PG8_BAR; PG8_SCHED;
	s_setprio 0
	s_add_i32 s76, s76, s88
	s_mov_b32 m0, s76
	ds_read_b128 v[172:175], v147 offset:49152
	ds_read_b128 v[180:183], v147 offset:50176
	ds_read_b128 v[184:187], v147 offset:51200
	ds_read_b128 v[188:191], v147 offset:52224
	ds_read_b128 v[192:195], v147 offset:53248
	ds_read_b128 v[196:199], v147 offset:54272
	ds_read_b128 v[200:203], v147 offset:55296
	ds_read_b128 v[210:213], v147 offset:56320
	s_add_u32 s58, s46, 0x80
	s_addc_u32 s59, s47, 0
	global_load_lds_dwordx4 v178, s[58:59]
	s_add_i32 m0, s76, 0x2000
	s_add_i32 s76, s77, s88
	s_add_u32 s60, s46, 0x40080
	s_addc_u32 s61, s47, 0
	global_load_lds_dwordx4 v178, s[60:61]
	s_mov_b32 m0, s76
	s_add_u32 s36, s46, 0x80080
	s_addc_u32 s37, s47, 0
	global_load_lds_dwordx4 v178, s[36:37]
	s_add_i32 m0, s76, 0x2000
	s_nop 0
	s_add_u32 s58, s46, 0xc0080
	s_addc_u32 s59, s47, 0
	global_load_lds_dwordx4 v178, s[58:59]
	s_mov_b32 m0, s93
	s_nop 0
	s_add_u32 s60, s80, 0x80
	s_addc_u32 s61, s81, 0
	global_load_lds_dwordx4 v134, s[60:61]
	s_mov_b32 m0, s94
	s_nop 0
	s_add_u32 s36, s80, 0x40080
	s_addc_u32 s37, s81, 0
	global_load_lds_dwordx4 v134, s[36:37]
	s_waitcnt vmcnt(8)
	s_waitcnt lgkmcnt(0)
	s_setprio 1
	s_barrier
	v_mfma_f32_16x16x32_bf16 v[62:65], v[130:133], v[172:175], v[62:65]
	v_mfma_f32_16x16x32_bf16 v[62:65], v[138:141], v[180:183], v[62:65]
	v_mfma_f32_16x16x32_bf16 v[54:57], v[152:155], v[180:183], v[54:57]
	v_mfma_f32_16x16x32_bf16 v[54:57], v[148:151], v[172:175], v[54:57]
	v_mfma_f32_16x16x32_bf16 v[38:41], v[148:151], v[184:187], v[38:41]
	v_mfma_f32_16x16x32_bf16 v[38:41], v[152:155], v[188:191], v[38:41]
	v_mfma_f32_16x16x32_bf16 v[46:49], v[138:141], v[188:191], v[46:49]
	v_mfma_f32_16x16x32_bf16 v[46:49], v[130:133], v[184:187], v[46:49]
	v_mfma_f32_16x16x32_bf16 v[30:33], v[130:133], v[192:195], v[30:33]
	v_mfma_f32_16x16x32_bf16 v[30:33], v[138:141], v[196:199], v[30:33]
	v_mfma_f32_16x16x32_bf16 v[22:25], v[152:155], v[196:199], v[22:25]
	v_mfma_f32_16x16x32_bf16 v[22:25], v[148:151], v[192:195], v[22:25]
	v_mfma_f32_16x16x32_bf16 v[6:9], v[148:151], v[200:203], v[6:9]
	v_mfma_f32_16x16x32_bf16 v[6:9], v[152:155], v[210:213], v[6:9]
	v_mfma_f32_16x16x32_bf16 v[14:17], v[138:141], v[210:213], v[14:17]
	v_mfma_f32_16x16x32_bf16 v[14:17], v[130:133], v[200:203], v[14:17]
	s_setprio 0
	s_setprio 1
	v_mfma_f32_16x16x32_bf16 v[2:5], v[164:167], v[200:203], v[2:5]
	v_mfma_f32_16x16x32_bf16 v[2:5], v[168:171], v[210:213], v[2:5]
	v_mfma_f32_16x16x32_bf16 v[50:53], v[168:171], v[180:183], v[50:53]
	v_mfma_f32_16x16x32_bf16 v[50:53], v[164:167], v[172:175], v[50:53]
	v_mfma_f32_16x16x32_bf16 v[58:61], v[156:159], v[172:175], v[58:61]
	v_mfma_f32_16x16x32_bf16 v[58:61], v[160:163], v[180:183], v[58:61]
	v_mfma_f32_16x16x32_bf16 v[42:45], v[160:163], v[188:191], v[42:45]
	v_mfma_f32_16x16x32_bf16 v[42:45], v[156:159], v[184:187], v[42:45]
	v_mfma_f32_16x16x32_bf16 v[34:37], v[164:167], v[184:187], v[34:37]
	v_mfma_f32_16x16x32_bf16 v[34:37], v[168:171], v[188:191], v[34:37]
	v_mfma_f32_16x16x32_bf16 v[18:21], v[168:171], v[196:199], v[18:21]
	v_mfma_f32_16x16x32_bf16 v[18:21], v[164:167], v[192:195], v[18:21]
	v_mfma_f32_16x16x32_bf16 v[26:29], v[156:159], v[192:195], v[26:29]
	v_mfma_f32_16x16x32_bf16 v[26:29], v[160:163], v[196:199], v[26:29]
	v_mfma_f32_16x16x32_bf16 v[10:13], v[160:163], v[210:213], v[10:13]
	v_mfma_f32_16x16x32_bf16 v[10:13], v[156:159], v[200:203], v[10:13]
	s_barrier
	s_setprio 0
	s_add_i32 s69, s69, 2
	s_add_u32 s62, s62, 0x100
	s_addc_u32 s63, s63, 0
	s_add_u32 s67, s67, 0x100
	s_addc_u32 s68, s68, 0
	s_cmp_gt_u32 s69, 29
	s_cbranch_scc0 .LBB0_705
	s_and_b64 vcc, exec, s[42:43]
	s_cbranch_vccz .LBB0_708
	s_barrier

; #define PG8_STAGE(bufoff, gbase, voff) do { _Pragma("unroll") for (int _i = 0; _i < 2; ++_i) \
;         __builtin_amdgcn_global_load_lds((const unsigned*)((const char*)(gbase) + (size_t)_i * qstep + (voff)[0]), (PG8_LAS unsigned*)(lds + (bufoff) + ldsw + _i * 8192), 16, 0, 0); } while (0)
; #define PG8_LDA(dst, b, h) do { _Pragma("unroll") for (int m = 0; m < 4; ++m) _Pragma("unroll") for (int k = 0; k < 2; ++k) dst[m][k] = *(const PG8_LAS bf16x8*)(lds + PG8_SA(b, h) + aoff + m * 2048 + k * 1024); } while (0)
; #define PG8_LDB(dst, b, h) do { _Pragma("unroll") for (int n = 0; n < 2; ++n) _Pragma("unroll") for (int k = 0; k < 2; ++k) dst[n][k] = *(const PG8_LAS bf16x8*)(lds + PG8_SB(b, h) + boff + n * 2048 + k * 1024); } while (0)
; #define PG8_WAIT_V89() do { if constexpr (SLIVER) PG8_WAIT_V(9); else PG8_WAIT_V(8); } while (0)
; #define PG8_WAIT_L(n) asm volatile("s_waitcnt lgkmcnt(" #n ")" ::: "memory")
; template <class Epi, class Sched, bool ALIGN_EPI = false, bool SP2 = false, bool SLIVER = false>
; __device__ __forceinline__ void gemm_phase(PG8_LAS unsigned char* lds, const Gemm g, const Sched& S, const Epi& E) {
;     ...
;         const bool has_next = S.next(ui + 1, nxt);
;         const char* nA = has_next ? (const char*)g.A + (size_t)nxt.pm * tstep + Epi::k0(nxt.seg) * 2 : cA; const char* nB = has_next ? (const char*)g.Bt + (size_t)nxt.pn * tstep + Epi::k0(nxt.seg) * 2 : cB;
;         const char* nS = has_next ? (const char*)g.A + (size_t)S.srow0 * K * 2 + (size_t)nxt.pm * sstep + Epi::k0(nxt.seg) * 2 : cS;
;         for (int t = 0; t < nt; t += 2) {
;             const bool last = (t == nt - 2);
;             const char* a1 = cA + (size_t)(t + 1) * kstep;
;             const char* a2 = last ? nA : cA + (size_t)(t + 2) * kstep; const char* b2 = last ? nB : cB + (size_t)(t + 2) * kstep;
;             const char* a3 = a2 + kstep; const char* b3 = b2 + kstep;
;             const char* s1 = cS + (size_t)(t + 1) * kstep; const char* s2 = last ? nS : cS + (size_t)(t + 2) * kstep;
;             if (last && has_next) S.a_ready(nxt);
;             if constexpr (SP2) {
;             PG8_LDB(B0, 0, 0); PG8_LDB(B1, 0, 1); PG8_SCHED; PG8_LDA(At, 0, 0); PG8_STAGE(PG8_SA(1, 1), a1 + hstep, voffA); PG8_STAGE_S(1, s1);
;             PG8_WAIT_V89(); PG8_WAIT_L(0); PG8_BAR; PG8_MMA(0, 0, At, B0); PG8_MMA(0, 1, At, B1); PG8_BAR; PG8_SCHED;
.LBB0_811:
	s_add_u32 s13, s90, s62
	s_addc_u32 s40, s91, s63
	s_add_u32 s13, s13, 0x100
	s_addc_u32 s66, s40, 0
	s_add_u32 s68, s2, s62
	s_addc_u32 s67, s3, s63
	s_add_i32 s69, 0, 0x10000
	s_cmpk_eq_i32 s62, 0x2b00
	s_cselect_b64 s[80:81], -1, 0
	s_and_b64 s[40:41], s[80:81], exec
	s_cselect_b32 s41, s85, s66
	s_cselect_b32 s40, s84, s13
	v_add_u32_e32 v66, s69, v220
	s_cselect_b32 s67, s87, s67
	s_cselect_b32 s66, s86, s68
	s_add_i32 s13, 0, 0x14000
	ds_read_b128 v[154:157], v66
	ds_read_b128 v[158:161], v66 offset:1024
	ds_read_b128 v[162:165], v66 offset:2048
	ds_read_b128 v[174:177], v66 offset:3072
	v_add_u32_e32 v66, s13, v220
	ds_read_b128 v[184:187], v66
	ds_read_b128 v[188:191], v66 offset:1024
	ds_read_b128 v[192:195], v66 offset:2048
	ds_read_b128 v[180:183], v66 offset:3072
	v_lshl_add_u64 v[146:147], v[214:215], 0, s[62:63]
	v_lshl_add_u64 v[148:149], v[146:147], 0, s[8:9]
	s_add_i32 m0, s19, 0xc000
	s_mov_b64 s[94:95], 0x210080
	ds_read_b128 v[66:69], v223
	ds_read_b128 v[70:73], v223 offset:1024
	ds_read_b128 v[74:77], v223 offset:2048
	ds_read_b128 v[78:81], v223 offset:3072
	ds_read_b128 v[216:219], v223 offset:4096
	ds_read_b128 v[224:227], v223 offset:5120
	ds_read_b128 v[228:231], v223 offset:6144
	ds_read_b128 v[232:235], v223 offset:7168
	global_load_lds_dwordx4 v[148:149], off
	v_lshl_add_u64 v[146:147], v[146:147], 0, s[94:95]
	s_add_i32 m0, s19, 0xe000
	s_nop 0
	global_load_lds_dwordx4 v[146:147], off
	v_lshl_add_u64 v[146:147], v[212:213], 0, s[62:63]
	s_add_i32 m0, s96, 0x20800
	s_nop 0
	global_load_lds_dword v[146:147], off
	s_waitcnt vmcnt(9)
	s_waitcnt lgkmcnt(0)
	s_setprio 1
	s_barrier
	v_mfma_f32_16x16x32_bf16 v[146:149], v[154:157], v[66:69], v[170:173]
	v_mfma_f32_16x16x32_bf16 v[146:149], v[158:161], v[70:73], v[146:149]
	v_mfma_f32_16x16x32_bf16 v[150:153], v[162:165], v[66:69], v[166:169]
	v_mfma_f32_16x16x32_bf16 v[150:153], v[174:177], v[70:73], v[150:153]
	v_mfma_f32_16x16x32_bf16 v[134:137], v[154:157], v[74:77], v[134:137]
	v_mfma_f32_16x16x32_bf16 v[134:137], v[158:161], v[78:81], v[134:137]
	v_mfma_f32_16x16x32_bf16 v[130:133], v[162:165], v[74:77], v[130:133]
	v_mfma_f32_16x16x32_bf16 v[130:133], v[174:177], v[78:81], v[130:133]
	v_mfma_f32_16x16x32_bf16 v[118:121], v[154:157], v[216:219], v[118:121]
	v_mfma_f32_16x16x32_bf16 v[118:121], v[158:161], v[224:227], v[118:121]
	v_mfma_f32_16x16x32_bf16 v[114:117], v[162:165], v[216:219], v[114:117]
	v_mfma_f32_16x16x32_bf16 v[114:117], v[174:177], v[224:227], v[114:117]
	v_mfma_f32_16x16x32_bf16 v[102:105], v[154:157], v[228:231], v[102:105]
	v_mfma_f32_16x16x32_bf16 v[102:105], v[158:161], v[232:235], v[102:105]
	v_mfma_f32_16x16x32_bf16 v[98:101], v[162:165], v[228:231], v[98:101]
	v_mfma_f32_16x16x32_bf16 v[98:101], v[174:177], v[232:235], v[98:101]
	s_setprio 0
	s_setprio 1
	v_mfma_f32_16x16x32_bf16 v[142:145], v[184:187], v[66:69], v[142:145]
	v_mfma_f32_16x16x32_bf16 v[142:145], v[188:191], v[70:73], v[142:145]
	v_mfma_f32_16x16x32_bf16 v[66:69], v[192:195], v[66:69], v[138:141]
	v_mfma_f32_16x16x32_bf16 v[138:141], v[180:183], v[70:73], v[66:69]
	v_mfma_f32_16x16x32_bf16 v[66:69], v[184:187], v[74:77], v[126:129]
	v_mfma_f32_16x16x32_bf16 v[126:129], v[188:191], v[78:81], v[66:69]
	v_mfma_f32_16x16x32_bf16 v[66:69], v[192:195], v[74:77], v[122:125]
	v_mfma_f32_16x16x32_bf16 v[122:125], v[180:183], v[78:81], v[66:69]
	v_mfma_f32_16x16x32_bf16 v[66:69], v[184:187], v[216:219], v[110:113]
	v_mfma_f32_16x16x32_bf16 v[110:113], v[188:191], v[224:227], v[66:69]
	v_mfma_f32_16x16x32_bf16 v[66:69], v[192:195], v[216:219], v[106:109]
	v_mfma_f32_16x16x32_bf16 v[106:109], v[180:183], v[224:227], v[66:69]
	v_mfma_f32_16x16x32_bf16 v[66:69], v[184:187], v[228:231], v[94:97]
	v_mfma_f32_16x16x32_bf16 v[94:97], v[188:191], v[232:235], v[66:69]
	v_mfma_f32_16x16x32_bf16 v[66:69], v[192:195], v[228:231], v[90:93]
	v_mfma_f32_16x16x32_bf16 v[90:93], v[180:183], v[232:235], v[66:69]
	s_barrier
; #define PG8_SB(B) __builtin_amdgcn_rcpf(1.f + expneg(B))
; #define PG8_SB(B) __builtin_amdgcn_rcpf(1.f + expneg(B))
; #define PG8_STAGE(bufoff, gbase, voff) do { _Pragma("unroll") for (int _i = 0; _i < 2; ++_i) \
;         __builtin_amdgcn_global_load_lds((const unsigned*)((const char*)(gbase) + (size_t)_i * qstep + (voff)[0]), (PG8_LAS unsigned*)(lds + (bufoff) + ldsw + _i * 8192), 16, 0, 0); } while (0)
; #define PG8_LDA(dst, b, h) do { _Pragma("unroll") for (int m = 0; m < 4; ++m) _Pragma("unroll") for (int k = 0; k < 2; ++k) dst[m][k] = *(const PG8_LAS bf16x8*)(lds + PG8_SA(b, h) + aoff + m * 2048 + k * 1024); } while (0)
; #define PG8_MMA(ai, bj, At, Bt) do { __builtin_amdgcn_s_setprio(1); _Pragma("unroll") for (int m = 0; m < 4; ++m) _Pragma("unroll") for (int n = 0; n < 2; ++n) _Pragma("unroll") for (int k = 0; k < 2; ++k) \
;         acc[ai][bj][m][n] = __builtin_amdgcn_mfma_f32_16x16x32_bf16(Bt[n][k], At[m][k], acc[ai][bj][m][n], 0, 0, 0); __builtin_amdgcn_s_setprio(0); } while (0)
; #define PG8_WAIT_V89() do { if constexpr (SLIVER) PG8_WAIT_V(9); else PG8_WAIT_V(8); } while (0)
; #define PG8_LDS_S(b) do { if constexpr (SLIVER) { Sf[0] = *(const PG8_LAS bf16x8*)(lds + STAGE_BYTES + (b) * 2048 + soff0); Sf[1] = *(const PG8_LAS bf16x8*)(lds + STAGE_BYTES + (b) * 2048 + (soff0 ^ 64)); } } while (0)
; #define PG8_WAIT_L(n) asm volatile("s_waitcnt lgkmcnt(" #n ")" ::: "memory")
; #define PG8_BAR __builtin_amdgcn_s_barrier()
; #define PG8_SCHED __builtin_amdgcn_sched_barrier(0)
; template <class Epi, class Sched, bool ALIGN_EPI = false, bool SP2 = false, bool SLIVER = false>
; __device__ __forceinline__ void gemm_phase(PG8_LAS unsigned char* lds, const Gemm g, const Sched& S, const Epi& E) {
;     ...
;             PG8_LDA(At, 0, 1); PG8_LDS_S(0); PG8_STAGE(PG8_SB(0, 0), b2, voffB); PG8_STAGE(PG8_SB(0, 1), b2 + hstep, voffB); PG8_STAGE(PG8_SA(0, 0), a2, voffA);
;             PG8_WAIT_V89(); PG8_WAIT_L(0); PG8_BAR; PG8_MMA(1, 0, At, B0); PG8_MMA(1, 1, At, B1); PG8_MMA_S(); PG8_BAR; PG8_SCHED;
	s_setprio 0
	s_add_i32 s68, 0, 0x20000
	v_lshl_add_u64 v[216:217], s[66:67], 0, v[198:199]
	s_add_i32 s66, s69, s18
	v_add_u32_e32 v74, s68, v221
	v_add_u32_e32 v75, s68, v222
	s_mov_b32 m0, s66
	ds_read_b128 v[66:69], v223 offset:16384
	ds_read_b128 v[70:73], v223 offset:17408
	ds_read_b128 v[224:227], v223 offset:18432
	ds_read_b128 v[228:231], v223 offset:19456
	ds_read_b128 v[232:235], v223 offset:20480
	ds_read_b128 v[240:243], v223 offset:21504
	ds_read_b128 v[244:247], v223 offset:22528
	ds_read_b128 v[248:251], v223 offset:23552
	ds_read_b128 v[166:169], v74
	ds_read_b128 v[170:173], v75
	global_load_lds_dwordx4 v[216:217], off
	v_lshl_add_u64 v[74:75], v[216:217], 0, s[64:65]
	s_add_i32 m0, s66, 0x2000
	s_add_i32 s13, s13, s18
	global_load_lds_dwordx4 v[74:75], off
	v_lshl_add_u64 v[74:75], v[216:217], 0, s[0:1]
	s_mov_b32 m0, s13
	v_lshl_add_u64 v[218:219], s[40:41], 0, v[196:197]
	global_load_lds_dwordx4 v[74:75], off
	v_lshl_add_u64 v[74:75], v[216:217], 0, s[74:75]
	s_add_i32 m0, s13, 0x2000
	s_nop 0
	global_load_lds_dwordx4 v[74:75], off
	s_mov_b32 m0, s19
	v_lshl_add_u64 v[74:75], v[218:219], 0, s[64:65]
	global_load_lds_dwordx4 v[218:219], off
	s_mov_b32 m0, s52
	s_nop 0
	global_load_lds_dwordx4 v[74:75], off
	s_waitcnt vmcnt(9)
	s_waitcnt lgkmcnt(0)
	s_setprio 1
	s_barrier
	v_mfma_f32_16x16x32_bf16 v[74:77], v[154:157], v[66:69], v[86:89]
	v_mfma_f32_16x16x32_bf16 v[74:77], v[158:161], v[70:73], v[74:77]
	v_mfma_f32_16x16x32_bf16 v[78:81], v[162:165], v[66:69], v[82:85]
	v_mfma_f32_16x16x32_bf16 v[78:81], v[174:177], v[70:73], v[78:81]
	v_mfma_f32_16x16x32_bf16 v[54:57], v[154:157], v[224:227], v[54:57]
	v_mfma_f32_16x16x32_bf16 v[54:57], v[158:161], v[228:231], v[54:57]
	v_mfma_f32_16x16x32_bf16 v[50:53], v[162:165], v[224:227], v[50:53]
	v_mfma_f32_16x16x32_bf16 v[50:53], v[174:177], v[228:231], v[50:53]
	v_mfma_f32_16x16x32_bf16 v[38:41], v[154:157], v[232:235], v[38:41]
	v_mfma_f32_16x16x32_bf16 v[38:41], v[158:161], v[240:243], v[38:41]
	v_mfma_f32_16x16x32_bf16 v[34:37], v[162:165], v[232:235], v[34:37]
	v_mfma_f32_16x16x32_bf16 v[34:37], v[174:177], v[240:243], v[34:37]
	v_mfma_f32_16x16x32_bf16 v[22:25], v[154:157], v[244:247], v[22:25]
	v_mfma_f32_16x16x32_bf16 v[22:25], v[158:161], v[248:251], v[22:25]
	v_mfma_f32_16x16x32_bf16 v[18:21], v[162:165], v[244:247], v[18:21]
	v_mfma_f32_16x16x32_bf16 v[18:21], v[174:177], v[248:251], v[18:21]
	s_setprio 0
	s_setprio 1
	v_mfma_f32_16x16x32_bf16 v[10:13], v[180:183], v[248:251], v[10:13]
	v_mfma_f32_16x16x32_bf16 v[10:13], v[192:195], v[244:247], v[10:13]
	v_mfma_f32_16x16x32_bf16 v[58:61], v[192:195], v[66:69], v[58:61]
	v_mfma_f32_16x16x32_bf16 v[58:61], v[180:183], v[70:73], v[58:61]
	v_mfma_f32_16x16x32_bf16 v[62:65], v[188:191], v[70:73], v[62:65]
	v_mfma_f32_16x16x32_bf16 v[62:65], v[184:187], v[66:69], v[62:65]
	v_mfma_f32_16x16x32_bf16 v[46:49], v[184:187], v[224:227], v[46:49]
	v_mfma_f32_16x16x32_bf16 v[46:49], v[188:191], v[228:231], v[46:49]
	v_mfma_f32_16x16x32_bf16 v[42:45], v[180:183], v[228:231], v[42:45]
	v_mfma_f32_16x16x32_bf16 v[42:45], v[192:195], v[224:227], v[42:45]
	v_mfma_f32_16x16x32_bf16 v[26:29], v[192:195], v[232:235], v[26:29]
	v_mfma_f32_16x16x32_bf16 v[26:29], v[180:183], v[240:243], v[26:29]
	v_mfma_f32_16x16x32_bf16 v[30:33], v[188:191], v[240:243], v[30:33]
	v_mfma_f32_16x16x32_bf16 v[30:33], v[184:187], v[232:235], v[30:33]
	v_mfma_f32_16x16x32_bf16 v[14:17], v[184:187], v[244:247], v[14:17]
	v_mfma_f32_16x16x32_bf16 v[14:17], v[188:191], v[248:251], v[14:17]
	s_setprio 0
	s_setprio 1
	s_and_b64 vcc, exec, s[82:83]
	s_cbranch_vccz .Lslv_b2
	v_mfma_f32_16x16x32_bf16 v[66:69], v[184:187], v[166:169], v[6:9]
	v_mfma_f32_16x16x32_bf16 v[70:73], v[192:195], v[166:169], v[2:5]
	v_mfma_f32_16x16x32_bf16 v[66:69], v[188:191], v[170:173], v[66:69]
	v_mfma_f32_16x16x32_bf16 v[70:73], v[180:183], v[170:173], v[70:73]
	s_branch .LBB0_815

; #define PG8_STAGE(bufoff, gbase, voff) do { _Pragma("unroll") for (int _i = 0; _i < 2; ++_i) \
;         __builtin_amdgcn_global_load_lds((const unsigned*)((const char*)(gbase) + (size_t)_i * qstep + (voff)[0]), (PG8_LAS unsigned*)(lds + (bufoff) + ldsw + _i * 8192), 16, 0, 0); } while (0)
; #define PG8_LDA(dst, b, h) do { _Pragma("unroll") for (int m = 0; m < 4; ++m) _Pragma("unroll") for (int k = 0; k < 2; ++k) dst[m][k] = *(const PG8_LAS bf16x8*)(lds + PG8_SA(b, h) + aoff + m * 2048 + k * 1024); } while (0)
; #define PG8_LDB(dst, b, h) do { _Pragma("unroll") for (int n = 0; n < 2; ++n) _Pragma("unroll") for (int k = 0; k < 2; ++k) dst[n][k] = *(const PG8_LAS bf16x8*)(lds + PG8_SB(b, h) + boff + n * 2048 + k * 1024); } while (0)
; #define PG8_WAIT_V89() do { if constexpr (SLIVER) PG8_WAIT_V(9); else PG8_WAIT_V(8); } while (0)
; #define PG8_WAIT_L(n) asm volatile("s_waitcnt lgkmcnt(" #n ")" ::: "memory")
; template <class Epi, class Sched, bool ALIGN_EPI = false, bool SP2 = false, bool SLIVER = false>
; __device__ __forceinline__ void gemm_phase(PG8_LAS unsigned char* lds, const Gemm g, const Sched& S, const Epi& E) {
;     ...
;         const bool has_next = S.next(ui + 1, nxt);
;         const char* nA = has_next ? (const char*)g.A + (size_t)nxt.pm * tstep + Epi::k0(nxt.seg) * 2 : cA; const char* nB = has_next ? (const char*)g.Bt + (size_t)nxt.pn * tstep + Epi::k0(nxt.seg) * 2 : cB;
;         const char* nS = has_next ? (const char*)g.A + (size_t)S.srow0 * K * 2 + (size_t)nxt.pm * sstep + Epi::k0(nxt.seg) * 2 : cS;
;         for (int t = 0; t < nt; t += 2) {
;             const bool last = (t == nt - 2);
;             const char* a1 = cA + (size_t)(t + 1) * kstep;
;             const char* a2 = last ? nA : cA + (size_t)(t + 2) * kstep; const char* b2 = last ? nB : cB + (size_t)(t + 2) * kstep;
;             const char* a3 = a2 + kstep; const char* b3 = b2 + kstep;
;             const char* s1 = cS + (size_t)(t + 1) * kstep; const char* s2 = last ? nS : cS + (size_t)(t + 2) * kstep;
;             if (last && has_next) S.a_ready(nxt);
;             if constexpr (SP2) {
;             PG8_LDB(B0, 0, 0); PG8_LDB(B1, 0, 1); PG8_SCHED; PG8_LDA(At, 0, 0); PG8_STAGE(PG8_SA(1, 1), a1 + hstep, voffA); PG8_STAGE_S(1, s1);
;             PG8_WAIT_V89(); PG8_WAIT_L(0); PG8_BAR; PG8_MMA(0, 0, At, B0); PG8_MMA(0, 1, At, B1); PG8_BAR; PG8_SCHED;
.LBB0_934:
	s_cmp_eq_u32 s66, s62
	s_cselect_b64 s[80:81], -1, 0
	s_add_u32 s12, s42, s62
	s_addc_u32 s13, s43, s63
	s_add_u32 s40, s12, 0x100
	s_addc_u32 s41, s13, 0
	s_and_b64 s[12:13], s[80:81], exec
	s_cselect_b32 s41, s95, s41
	s_cselect_b32 s40, s94, s40
	s_add_u32 s68, s17, s62
	s_addc_u32 s69, s45, s63
	s_add_i32 s76, 0, 0x10000
	s_and_b64 s[12:13], s[80:81], exec
	v_add_u32_e32 v138, s76, v212
	s_cselect_b32 s13, s97, s69
	s_cselect_b32 s12, s96, s68
	s_add_i32 s68, 0, 0x14000
	ds_read_b128 v[146:149], v138
	ds_read_b128 v[150:153], v138 offset:1024
	ds_read_b128 v[154:157], v138 offset:2048
	ds_read_b128 v[158:161], v138 offset:3072
	v_add_u32_e32 v138, s68, v212
	ds_read_b128 v[166:169], v138
	ds_read_b128 v[170:173], v138 offset:1024
	ds_read_b128 v[174:177], v138 offset:2048
	ds_read_b128 v[162:165], v138 offset:3072
	v_lshl_add_u64 v[202:203], v[198:199], 0, s[62:63]
	s_mov_b64 vcc, 0x90080
	v_lshl_add_u64 v[208:209], v[202:203], 0, vcc
	s_add_i32 m0, s93, 0xc000
	s_mov_b64 vcc, 0xd8080
	ds_read_b128 v[138:141], v215
	ds_read_b128 v[142:145], v215 offset:1024
	ds_read_b128 v[180:183], v215 offset:2048
	ds_read_b128 v[184:187], v215 offset:3072
	ds_read_b128 v[216:219], v215 offset:4096
	ds_read_b128 v[220:223], v215 offset:5120
	ds_read_b128 v[224:227], v215 offset:6144
	ds_read_b128 v[228:231], v215 offset:7168
	global_load_lds_dwordx4 v[208:209], off
	v_lshl_add_u64 v[202:203], v[202:203], 0, vcc
	s_add_i32 m0, s93, 0xe000
	s_nop 0
	global_load_lds_dwordx4 v[202:203], off
	v_lshl_add_u64 v[202:203], v[200:201], 0, s[62:63]
	s_add_i32 m0, s50, 0x20800
	s_nop 0
	global_load_lds_dword v[202:203], off
	s_waitcnt vmcnt(9)
	s_waitcnt lgkmcnt(0)
	s_setprio 1
	s_barrier
	v_mfma_f32_16x16x32_bf16 v[134:137], v[146:149], v[138:141], v[134:137]
	v_mfma_f32_16x16x32_bf16 v[134:137], v[150:153], v[142:145], v[134:137]
	v_mfma_f32_16x16x32_bf16 v[130:133], v[158:161], v[142:145], v[130:133]
	v_mfma_f32_16x16x32_bf16 v[130:133], v[154:157], v[138:141], v[130:133]
	v_mfma_f32_16x16x32_bf16 v[122:125], v[154:157], v[180:183], v[122:125]
	v_mfma_f32_16x16x32_bf16 v[122:125], v[158:161], v[184:187], v[122:125]
	v_mfma_f32_16x16x32_bf16 v[126:129], v[150:153], v[184:187], v[126:129]
	v_mfma_f32_16x16x32_bf16 v[126:129], v[146:149], v[180:183], v[126:129]
	v_mfma_f32_16x16x32_bf16 v[114:117], v[146:149], v[216:219], v[114:117]
	v_mfma_f32_16x16x32_bf16 v[114:117], v[150:153], v[220:223], v[114:117]
	v_mfma_f32_16x16x32_bf16 v[106:109], v[158:161], v[220:223], v[106:109]
	v_mfma_f32_16x16x32_bf16 v[106:109], v[154:157], v[216:219], v[106:109]
	v_mfma_f32_16x16x32_bf16 v[90:93], v[154:157], v[224:227], v[90:93]
	v_mfma_f32_16x16x32_bf16 v[90:93], v[158:161], v[228:231], v[90:93]
	v_mfma_f32_16x16x32_bf16 v[98:101], v[150:153], v[228:231], v[98:101]
	v_mfma_f32_16x16x32_bf16 v[98:101], v[146:149], v[224:227], v[98:101]
	s_setprio 0
	s_setprio 1
	v_mfma_f32_16x16x32_bf16 v[74:77], v[174:177], v[224:227], v[74:77]
	v_mfma_f32_16x16x32_bf16 v[74:77], v[162:165], v[228:231], v[74:77]
	v_mfma_f32_16x16x32_bf16 v[110:113], v[162:165], v[142:145], v[110:113]
	v_mfma_f32_16x16x32_bf16 v[110:113], v[174:177], v[138:141], v[110:113]
	v_mfma_f32_16x16x32_bf16 v[118:121], v[166:169], v[138:141], v[118:121]
	v_mfma_f32_16x16x32_bf16 v[118:121], v[170:173], v[142:145], v[118:121]
	v_mfma_f32_16x16x32_bf16 v[102:105], v[170:173], v[184:187], v[102:105]
	v_mfma_f32_16x16x32_bf16 v[102:105], v[166:169], v[180:183], v[102:105]
	v_mfma_f32_16x16x32_bf16 v[94:97], v[174:177], v[180:183], v[94:97]
	v_mfma_f32_16x16x32_bf16 v[94:97], v[162:165], v[184:187], v[94:97]
	v_mfma_f32_16x16x32_bf16 v[82:85], v[162:165], v[220:223], v[82:85]
	v_mfma_f32_16x16x32_bf16 v[82:85], v[174:177], v[216:219], v[82:85]
	v_mfma_f32_16x16x32_bf16 v[86:89], v[166:169], v[216:219], v[86:89]
	v_mfma_f32_16x16x32_bf16 v[86:89], v[170:173], v[220:223], v[86:89]
	v_mfma_f32_16x16x32_bf16 v[78:81], v[170:173], v[228:231], v[78:81]
	v_mfma_f32_16x16x32_bf16 v[78:81], v[166:169], v[224:227], v[78:81]
	s_barrier
; #define PG8_SB(B) __builtin_amdgcn_rcpf(1.f + expneg(B))
; #define PG8_SB(B) __builtin_amdgcn_rcpf(1.f + expneg(B))
; #define PG8_STAGE(bufoff, gbase, voff) do { _Pragma("unroll") for (int _i = 0; _i < 2; ++_i) \
;         __builtin_amdgcn_global_load_lds((const unsigned*)((const char*)(gbase) + (size_t)_i * qstep + (voff)[0]), (PG8_LAS unsigned*)(lds + (bufoff) + ldsw + _i * 8192), 16, 0, 0); } while (0)
; #define PG8_LDA(dst, b, h) do { _Pragma("unroll") for (int m = 0; m < 4; ++m) _Pragma("unroll") for (int k = 0; k < 2; ++k) dst[m][k] = *(const PG8_LAS bf16x8*)(lds + PG8_SA(b, h) + aoff + m * 2048 + k * 1024); } while (0)
; #define PG8_MMA(ai, bj, At, Bt) do { __builtin_amdgcn_s_setprio(1); _Pragma("unroll") for (int m = 0; m < 4; ++m) _Pragma("unroll") for (int n = 0; n < 2; ++n) _Pragma("unroll") for (int k = 0; k < 2; ++k) \
;         acc[ai][bj][m][n] = __builtin_amdgcn_mfma_f32_16x16x32_bf16(Bt[n][k], At[m][k], acc[ai][bj][m][n], 0, 0, 0); __builtin_amdgcn_s_setprio(0); } while (0)
; #define PG8_WAIT_V89() do { if constexpr (SLIVER) PG8_WAIT_V(9); else PG8_WAIT_V(8); } while (0)
; #define PG8_LDS_S(b) do { if constexpr (SLIVER) { Sf[0] = *(const PG8_LAS bf16x8*)(lds + STAGE_BYTES + (b) * 2048 + soff0); Sf[1] = *(const PG8_LAS bf16x8*)(lds + STAGE_BYTES + (b) * 2048 + (soff0 ^ 64)); } } while (0)
; #define PG8_WAIT_L(n) asm volatile("s_waitcnt lgkmcnt(" #n ")" ::: "memory")
; #define PG8_BAR __builtin_amdgcn_s_barrier()
; #define PG8_SCHED __builtin_amdgcn_sched_barrier(0)
; template <class Epi, class Sched, bool ALIGN_EPI = false, bool SP2 = false, bool SLIVER = false>
; __device__ __forceinline__ void gemm_phase(PG8_LAS unsigned char* lds, const Gemm g, const Sched& S, const Epi& E) {
;     ...
;             PG8_LDA(At, 0, 1); PG8_LDS_S(0); PG8_STAGE(PG8_SB(0, 0), b2, voffB); PG8_STAGE(PG8_SB(0, 1), b2 + hstep, voffB); PG8_STAGE(PG8_SA(0, 0), a2, voffA);
;             PG8_WAIT_V89(); PG8_WAIT_L(0); PG8_BAR; PG8_MMA(1, 0, At, B0); PG8_MMA(1, 1, At, B1); PG8_MMA_S(); PG8_BAR; PG8_SCHED;
	s_setprio 0
	s_add_i32 s69, 0, 0x20000
	v_lshl_add_u64 v[202:203], s[12:13], 0, v[190:191]
	s_add_i32 s12, s76, s92
	v_add_u32_e32 v178, s69, v213
	v_add_u32_e32 v184, s69, v214
	s_mov_b32 m0, s12
	ds_read_b128 v[138:141], v215 offset:16384
	ds_read_b128 v[142:145], v215 offset:17408
	ds_read_b128 v[216:219], v215 offset:18432
	ds_read_b128 v[220:223], v215 offset:19456
	ds_read_b128 v[224:227], v215 offset:20480
	ds_read_b128 v[228:231], v215 offset:21504
	ds_read_b128 v[232:235], v215 offset:22528
	ds_read_b128 v[240:243], v215 offset:23552
	ds_read_b128 v[180:183], v178
	ds_read_b128 v[184:187], v184
	global_load_lds_dwordx4 v[202:203], off
	v_lshl_add_u64 v[208:209], v[202:203], 0, s[70:71]
	s_add_i32 m0, s12, 0x2000
	s_add_i32 s12, s68, s92
	global_load_lds_dwordx4 v[208:209], off
	v_lshl_add_u64 v[208:209], v[202:203], 0, s[46:47]
	s_mov_b32 m0, s12
	v_lshl_add_u64 v[210:211], s[40:41], 0, v[188:189]
	global_load_lds_dwordx4 v[208:209], off
	v_lshl_add_u64 v[208:209], v[202:203], 0, s[6:7]
	s_add_i32 m0, s12, 0x2000
	s_nop 0
	global_load_lds_dwordx4 v[208:209], off
	s_mov_b32 m0, s93
	v_lshl_add_u64 v[208:209], v[210:211], 0, s[70:71]
	global_load_lds_dwordx4 v[210:211], off
	s_mov_b32 m0, s48
	s_nop 0
	global_load_lds_dwordx4 v[208:209], off
	s_waitcnt vmcnt(9)
	s_waitcnt lgkmcnt(0)
	s_setprio 1
	s_barrier
	v_mfma_f32_16x16x32_bf16 v[70:73], v[146:149], v[138:141], v[70:73]
	v_mfma_f32_16x16x32_bf16 v[70:73], v[150:153], v[142:145], v[70:73]
	v_mfma_f32_16x16x32_bf16 v[66:69], v[158:161], v[142:145], v[66:69]
	v_mfma_f32_16x16x32_bf16 v[66:69], v[154:157], v[138:141], v[66:69]
	v_mfma_f32_16x16x32_bf16 v[58:61], v[154:157], v[216:219], v[58:61]
	v_mfma_f32_16x16x32_bf16 v[58:61], v[158:161], v[220:223], v[58:61]
	v_mfma_f32_16x16x32_bf16 v[62:65], v[150:153], v[220:223], v[62:65]
	v_mfma_f32_16x16x32_bf16 v[62:65], v[146:149], v[216:219], v[62:65]
	v_mfma_f32_16x16x32_bf16 v[50:53], v[146:149], v[224:227], v[50:53]
	v_mfma_f32_16x16x32_bf16 v[50:53], v[150:153], v[228:231], v[50:53]
	v_mfma_f32_16x16x32_bf16 v[42:45], v[158:161], v[228:231], v[42:45]
	v_mfma_f32_16x16x32_bf16 v[42:45], v[154:157], v[224:227], v[42:45]
	v_mfma_f32_16x16x32_bf16 v[26:29], v[154:157], v[232:235], v[26:29]
	v_mfma_f32_16x16x32_bf16 v[26:29], v[158:161], v[240:243], v[26:29]
	v_mfma_f32_16x16x32_bf16 v[34:37], v[150:153], v[240:243], v[34:37]
	v_mfma_f32_16x16x32_bf16 v[34:37], v[146:149], v[232:235], v[34:37]
	s_setprio 0
	s_setprio 1
	v_mfma_f32_16x16x32_bf16 v[10:13], v[174:177], v[232:235], v[10:13]
	v_mfma_f32_16x16x32_bf16 v[10:13], v[162:165], v[240:243], v[10:13]
	v_mfma_f32_16x16x32_bf16 v[46:49], v[162:165], v[142:145], v[46:49]
	v_mfma_f32_16x16x32_bf16 v[46:49], v[174:177], v[138:141], v[46:49]
	v_mfma_f32_16x16x32_bf16 v[54:57], v[166:169], v[138:141], v[54:57]
	v_mfma_f32_16x16x32_bf16 v[54:57], v[170:173], v[142:145], v[54:57]
	v_mfma_f32_16x16x32_bf16 v[38:41], v[170:173], v[220:223], v[38:41]
	v_mfma_f32_16x16x32_bf16 v[38:41], v[166:169], v[216:219], v[38:41]
	v_mfma_f32_16x16x32_bf16 v[30:33], v[174:177], v[216:219], v[30:33]
	v_mfma_f32_16x16x32_bf16 v[30:33], v[162:165], v[220:223], v[30:33]
	v_mfma_f32_16x16x32_bf16 v[18:21], v[162:165], v[228:231], v[18:21]
	v_mfma_f32_16x16x32_bf16 v[18:21], v[174:177], v[224:227], v[18:21]
	v_mfma_f32_16x16x32_bf16 v[22:25], v[166:169], v[224:227], v[22:25]
	v_mfma_f32_16x16x32_bf16 v[22:25], v[170:173], v[228:231], v[22:25]
	v_mfma_f32_16x16x32_bf16 v[14:17], v[170:173], v[240:243], v[14:17]
	v_mfma_f32_16x16x32_bf16 v[14:17], v[166:169], v[232:235], v[14:17]
	s_setprio 0
	s_setprio 1
	s_and_b64 vcc, exec, s[90:91]
	s_cbranch_vccz .Lslv_b3
	v_mfma_f32_16x16x32_bf16 v[138:141], v[166:169], v[180:183], v[6:9]
	v_mfma_f32_16x16x32_bf16 v[142:145], v[174:177], v[180:183], v[2:5]
	v_mfma_f32_16x16x32_bf16 v[138:141], v[170:173], v[184:187], v[138:141]
	v_mfma_f32_16x16x32_bf16 v[142:145], v[162:165], v[184:187], v[142:145]
	s_branch .LBB0_938
